# out-proj L0: third-round tiles split in two along K (16 CUs/XCD, 8 K-steps each), K-half 1 writes gate*acc to a partial buffer that LayerNorm adds
# speedup vs baseline: 1.0113x; 1.0113x over previous
; DI void phase_ln(const P& p, int l) {
;     ...
;   for (int row = r0; row < r1; row += 2) {
;     const bool two = row + 1 < r1;
;     const int rowb = two ? row + 1 : row;
;     float4 v[2][4];
; #pragma unroll
;     for (int i = 0; i < 4; ++i) {
;       v[0][i] = *(const float4*)(Zb + (size_t)row * 1024 + i * 256 + lane * 4);
;       v[1][i] = *(const float4*)(Zb + (size_t)rowb * 1024 + i * 256 + lane * 4);
;     }
.Lln_nopf:
	v_add_u32_e32 v63, 1, v62
	v_cmp_lt_i32_e64 s[40:41], v63, v65
	v_lshl_add_u64 v[90:91], v[80:81], 0, v[78:79]
	v_cmp_gt_i32_e32 vcc, s21, v62
	v_cndmask_b32_e64 v86, v62, v63, s[40:41]
	v_ashrrev_i32_e32 v87, 31, v86
	v_lshlrev_b64 v[88:89], 12, v[86:87]
	v_lshl_add_u64 v[38:39], v[66:67], 0, v[88:89]
	v_readfirstlane_b32 s98, v62
	s_lshr_b32 s98, s98, 8
	s_mul_i32 s99, s98, 0xe39
	s_lshr_b32 s99, s99, 16
	s_mul_i32 s100, s99, 18
	s_sub_i32 s98, s98, s100
	s_lshl_b32 s99, s99, 24
	s_sub_u32 s100, 0x8000000, s99
	s_mov_b32 s101, 0
	v_lshl_add_u64 v[228:229], v[90:91], 0, s[100:101]
	v_lshl_add_u64 v[230:231], v[38:39], 0, s[100:101]
	global_load_dwordx4 v[34:37], v[38:39], off
	global_load_dwordx4 v[46:49], v[38:39], off offset:1024
	global_load_dwordx4 v[42:45], v[38:39], off offset:2048
	s_nop 0
	global_load_dwordx4 v[38:41], v[38:39], off offset:3072
	s_nop 0
	global_load_dwordx4 v[50:53], v[90:91], off offset:3072
	global_load_dwordx4 v[54:57], v[90:91], off offset:2048
	global_load_dwordx4 v[58:61], v[90:91], off offset:1024
	s_cmp_lg_u32 s50, 0
	s_cbranch_scc1 .Lln_nosplit
	s_cmp_lt_u32 s98, 16
	s_cbranch_scc1 .Lln_nosplit
	global_load_dwordx4 v[196:199], v[228:229], off
	global_load_dwordx4 v[200:203], v[228:229], off offset:1024
	global_load_dwordx4 v[204:207], v[228:229], off offset:2048
	global_load_dwordx4 v[208:211], v[228:229], off offset:3072
	global_load_dwordx4 v[212:215], v[230:231], off
	global_load_dwordx4 v[216:219], v[230:231], off offset:1024
	global_load_dwordx4 v[220:223], v[230:231], off offset:2048
	global_load_dwordx4 v[232:235], v[230:231], off offset:3072
	s_waitcnt vmcnt(0)
	v_pk_add_f32 v[58:59], v[58:59], v[200:201]
	v_pk_add_f32 v[60:61], v[60:61], v[202:203]
	v_pk_add_f32 v[54:55], v[54:55], v[204:205]
	v_pk_add_f32 v[56:57], v[56:57], v[206:207]
	v_pk_add_f32 v[50:51], v[50:51], v[208:209]
	v_pk_add_f32 v[52:53], v[52:53], v[210:211]
	v_pk_add_f32 v[34:35], v[34:35], v[212:213]
	v_pk_add_f32 v[36:37], v[36:37], v[214:215]
	v_pk_add_f32 v[46:47], v[46:47], v[216:217]
	v_pk_add_f32 v[48:49], v[48:49], v[218:219]
	v_pk_add_f32 v[42:43], v[42:43], v[220:221]
	v_pk_add_f32 v[44:45], v[44:45], v[222:223]
	v_pk_add_f32 v[38:39], v[38:39], v[232:233]
	v_pk_add_f32 v[40:41], v[40:41], v[234:235]
	s_branch .Lln_splitdone
.Lln_nosplit:
	v_mov_b32_e32 v196, 0
	v_mov_b32_e32 v197, 0
	v_mov_b32_e32 v198, 0
	v_mov_b32_e32 v199, 0
; DI void phase_ln(const P& p, int l) {
;     ...
; #pragma unroll
;     for (int h = 0; h < 2; ++h) {
;       if (h && !two) break;
;       const int rr = h ? rowb : row;
;       float s = 0.f;
; #pragma unroll
;       for (int i = 0; i < 4; ++i) s += (v[h][i].x + v[h][i].y) + (v[h][i].z + v[h][i].w);
; #pragma unroll
;       for (int o = 32; o >= 1; o >>= 1) s += __shfl_xor(s, o);
;       const float mean = s * (1.f / 1024.f);
;       float q = 0.f;
; #pragma unroll
;       for (int i = 0; i < 4; ++i) {
;         v[h][i].x -= mean; v[h][i].y -= mean; v[h][i].z -= mean; v[h][i].w -= mean;
;         q += (v[h][i].x * v[h][i].x + v[h][i].y * v[h][i].y) + (v[h][i].z * v[h][i].z + v[h][i].w * v[h][i].w);
;       }
; #pragma unroll
;       for (int o = 32; o >= 1; o >>= 1) q += __shfl_xor(q, o);
;       const float rstd = rsqrtf(q * (1.f / 1024.f) + 1e-5f);
;       const int mr = rr < MLAT ? (rr >> 11) : 16;
;       const float* md = p.mod + (size_t)(1 * 17 + mr) * 3072;
; #pragma unroll
;       for (int i = 0; i < 4; ++i) {
;         const int col = i * 256 + lane * 4;
;         float4 y;
;         y.x = v[h][i].x * rstd * g4[i].x + b4[i].x;
;         y.y = v[h][i].y * rstd * g4[i].y + b4[i].y;
;         y.z = v[h][i].z * rstd * g4[i].z + b4[i].z;
;         y.w = v[h][i].w * rstd * g4[i].w + b4[i].w;
;         if (l == 1 || rr < MLAT) *(float4*)(p.out + (size_t)rr * 1024 + col) = y;
.Lln_splitdone:
	s_or_b64 s[52:53], s[46:47], vcc
	s_waitcnt vmcnt(1)
	v_mov_b32_e32 v0, v57
	s_waitcnt vmcnt(0)
	v_mov_b32_e32 v92, v58
	v_mov_b32_e32 v93, v60
	v_mov_b32_e32 v98, v59
	v_mov_b32_e32 v99, v61
	v_pk_add_f32 v[92:93], v[92:93], v[98:99]
	v_pk_add_f32 v[94:95], v[56:57], v[0:1]
	v_pk_add_f32 v[98:99], v[92:93], v[92:93] op_sel:[0,1] op_sel_hi:[1,0]
	global_load_dwordx4 v[90:93], v[90:91], off
	v_mov_b32_e32 v0, v55
	v_pk_add_f32 v[96:97], v[54:55], v[0:1]
	v_mov_b32_e32 v95, v53
	v_mov_b32_e32 v97, v52
	v_mov_b32_e32 v99, v51
	v_pk_add_f32 v[94:95], v[96:97], v[94:95]
	s_waitcnt vmcnt(0)
	v_pk_add_f32 v[90:91], v[90:91], v[196:197]
	v_pk_add_f32 v[92:93], v[92:93], v[198:199]
	v_mov_b32_e32 v100, v90
	v_mov_b32_e32 v101, v92
	v_mov_b32_e32 v106, v91
	v_mov_b32_e32 v107, v93
	v_pk_add_f32 v[100:101], v[100:101], v[106:107]
	s_nop 0
	v_add_f32_e32 v0, v100, v101
	v_add_f32_e32 v100, 0, v0
	v_mov_b32_e32 v101, v50
	v_pk_add_f32 v[96:97], v[100:101], v[98:99]
	s_nop 0
	v_pk_add_f32 v[94:95], v[96:97], v[94:95]
	s_nop 0
	v_add_f32_e32 v0, v94, v95
	v_mov_b32_e32 v94, v0
	s_nop 1
	v_permlane32_swap_b32_e32 v0, v94
	v_add_f32_e32 v0, v0, v94
	v_mov_b32_e32 v94, v0
	s_nop 1
	v_permlane16_swap_b32_e32 v0, v94
	v_add_f32_e32 v0, v0, v94
	s_nop 1
	v_add_f32_dpp v0, v0, v0 row_ror:8 row_mask:0xf bank_mask:0xf
	s_nop 1
	v_mov_b32_dpp v94, v0 row_shl:4 row_mask:0xf bank_mask:0x5
	v_mov_b32_dpp v94, v0 row_shr:4 row_mask:0xf bank_mask:0xa
	v_add_f32_e32 v0, v0, v94
	s_nop 1
	v_add_f32_dpp v0, v0, v0 quad_perm:[2,3,0,1] row_mask:0xf bank_mask:0xf
	s_nop 1
	v_add_f32_dpp v0, v0, v0 quad_perm:[1,0,3,2] row_mask:0xf bank_mask:0xf
	v_mul_f32_e32 v0, 0x3a800000, v0
	v_pk_add_f32 v[96:97], v[90:91], v[0:1] op_sel_hi:[1,0] neg_lo:[0,1] neg_hi:[0,1]
	v_pk_add_f32 v[98:99], v[92:93], v[0:1] op_sel_hi:[1,0] neg_lo:[0,1] neg_hi:[0,1]
	v_mov_b32_e32 v92, v97
	v_mov_b32_e32 v93, v99
	v_mov_b32_e32 v90, v96
	v_mov_b32_e32 v91, v98
	v_pk_mul_f32 v[92:93], v[92:93], v[92:93]
	s_nop 0
	v_pk_fma_f32 v[90:91], v[90:91], v[90:91], v[92:93]
	v_pk_add_f32 v[92:93], v[58:59], v[0:1] op_sel_hi:[1,0] neg_lo:[0,1] neg_hi:[0,1]
	v_pk_add_f32 v[94:95], v[90:91], v[90:91] op_sel_hi:[0,1]
	v_pk_add_f32 v[90:91], v[60:61], v[0:1] op_sel_hi:[1,0] neg_lo:[0,1] neg_hi:[0,1]
	v_mov_b32_e32 v60, v93
	v_mov_b32_e32 v61, v91
	v_mov_b32_e32 v58, v92
	v_mov_b32_e32 v59, v90
	v_pk_mul_f32 v[60:61], v[60:61], v[60:61]
	s_nop 0
	v_pk_fma_f32 v[58:59], v[58:59], v[58:59], v[60:61]
	v_pk_add_f32 v[60:61], v[54:55], v[0:1] op_sel_hi:[1,0] neg_lo:[0,1] neg_hi:[0,1]
	v_pk_add_f32 v[100:101], v[58:59], v[58:59] op_sel_hi:[0,1]
	v_pk_add_f32 v[58:59], v[56:57], v[0:1] op_sel_hi:[1,0] neg_lo:[0,1] neg_hi:[0,1]
	v_mul_f32_e32 v54, v60, v60
	v_pk_fma_f32 v[106:107], v[60:61], v[60:61], v[54:55] op_sel_hi:[1,1,0]
	v_mul_f32_e32 v54, v58, v58
	v_pk_fma_f32 v[108:109], v[58:59], v[58:59], v[54:55] op_sel_hi:[1,1,0]
	v_pk_add_f32 v[56:57], v[50:51], v[0:1] op_sel_hi:[1,0] neg_lo:[0,1] neg_hi:[0,1]
	v_pk_add_f32 v[54:55], v[52:53], v[0:1] op_sel_hi:[1,0] neg_lo:[0,1] neg_hi:[0,1]
	v_pk_mul_f32 v[50:51], v[56:57], v[56:57]
	v_pk_mul_f32 v[52:53], v[54:55], v[54:55]
	v_mov_b32_e32 v106, v50
	v_mov_b32_e32 v108, v51
	v_mov_b32_e32 v94, v52
	v_mov_b32_e32 v100, v53
	v_pk_add_f32 v[50:51], v[106:107], v[108:109]
	v_pk_add_f32 v[52:53], v[94:95], v[100:101]
	s_nop 0
	v_pk_add_f32 v[50:51], v[50:51], v[52:53]
	s_nop 0
	v_add_f32_e32 v0, v50, v51
	v_mov_b32_e32 v50, v0
	s_nop 1
	v_permlane32_swap_b32_e32 v0, v50
	v_add_f32_e32 v0, v0, v50
	v_mov_b32_e32 v50, v0
	s_nop 1
	v_permlane16_swap_b32_e32 v0, v50
	v_add_f32_e32 v0, v0, v50
	s_nop 1
	v_add_f32_dpp v0, v0, v0 row_ror:8 row_mask:0xf bank_mask:0xf
	s_nop 1
	v_mov_b32_dpp v50, v0 row_shl:4 row_mask:0xf bank_mask:0x5
	v_mov_b32_dpp v50, v0 row_shr:4 row_mask:0xf bank_mask:0xa
	v_add_f32_e32 v0, v0, v50
	s_nop 1
	v_add_f32_dpp v0, v0, v0 quad_perm:[2,3,0,1] row_mask:0xf bank_mask:0xf
	s_nop 1
	v_add_f32_dpp v0, v0, v0 quad_perm:[1,0,3,2] row_mask:0xf bank_mask:0xf
	v_mov_b32_e32 v50, 0x3727c5ac
	v_fmamk_f32 v0, v0, 0x3a800000, v50
	v_cmp_gt_f32_e32 vcc, s37, v0
	v_mul_f32_e32 v50, 0x4b800000, v0
	s_nop 0
	v_cndmask_b32_e32 v0, v0, v50, vcc
	v_rsq_f32_e32 v0, v0
	s_nop 0
	v_mul_f32_e32 v50, 0x45800000, v0
	v_cndmask_b32_e32 v94, v0, v50, vcc
	v_pk_mul_f32 v[50:51], v[96:97], v[94:95] op_sel_hi:[1,0]
	v_pk_mul_f32 v[52:53], v[98:99], v[94:95] op_sel_hi:[1,0]
	v_pk_fma_f32 v[50:51], v[2:3], v[50:51], v[10:11]
	v_pk_fma_f32 v[52:53], v[4:5], v[52:53], v[12:13]
	v_lshl_add_u64 v[96:97], v[82:83], 0, v[78:79]
	s_and_saveexec_b64 s[42:43], s[52:53]
	s_cbranch_execz .LBB0_34
	global_store_dwordx4 v[96:97], v[50:53], off

; template <int EPI>
; DI bool tile_coords(int j, int mpx, int& m0, int& n0) {
;     ...
;     if (q >= mpx * 4) return false;
; DI void phase_outproj(const P& p, int l, char* lds) {
;   const int mrows = (l == 0) ? MALL : MLAT;
;   gemm_phase<1>(p, l, p.H  , p.Wot + (size_t)l * 1024 * 1024, (mrows / 256) / 8, lds);
; __global__ void __launch_bounds__(512, 2) mega(P p) {
;     ...
;       else if (s == 2) { for (int rr = 0; rr < REP_OUT; ++rr) { if (rr) cg::this_grid().sync(); phase_outproj(p, l, lds); } }
.LBB0_66:
	s_andn2_b64 vcc, exec, s[0:1]
	s_cbranch_vccnz .LBB0_73
	s_cmp_lt_u32 s23, 4
	s_cselect_b64 s[0:1], -1, 0
	s_and_b64 s[26:27], s[0:1], exec
	s_cselect_b32 s2, 18, 16
	s_lshl_b32 s25, s2, 2
	s_cmp_lt_u32 s84, s25
	v_mov_b32_e32 v0, v195
	s_cbranch_scc0 .LBB0_73
	s_cmp_lg_u32 s50, 0
	s_cbranch_scc1 .Ldephase_out_done
	s_cmp_lt_u32 s84, 16
	s_cbranch_scc1 .Ldephase_out_done
	s_sleep 127
	s_sleep 127
	s_sleep 127
	s_sleep 127

; template <int EPI>
; DI bool tile_coords(int j, int mpx, int& m0, int& n0) {
;   const int x = blockIdx.x & 7, s = blockIdx.x >> 3, ns = gridDim.x >> 3;
;   const int q = s + ns * j;
;   if constexpr (EPI == 0) {
;     if (q >= mpx * 15) return false;
;     const int panel = q / 90, i = q % 90;
;     const int nt = i / 6, mi = i % 6;
;     m0 = (x * mpx + panel * 6 + mi) * 256;
;     n0 = nt * 256;
;   } else {
;     if (q >= mpx * 4) return false;
;     m0 = (x * mpx + (q >> 2)) * 256;
;     n0 = (q & 3) * 256;
;   }
;   return true;
; template <int EPI>
; DI void gemm_phase(const P& p, int l, const u16* __restrict__ A, const u16* __restrict__ Bt, int mpx, char* lds) {
;     ...
;   while (true) {
;   const int tn = t + 1;
;   int m1 = 0, n1 = 0;
;   const bool has_next = tile_coords<EPI>(tn, mpx, m1, n1);
;   const u16* Agn = A + (size_t)m1 * 1024;
;   const u16* Bgn = Bt + (size_t)n1 * 1024;
;   f32x4 acc[8][4];
; #pragma unroll
;   for (int i = 0; i < 8; ++i)
; #pragma unroll
;     for (int j = 0; j < 4; ++j) acc[i][j] = zero4();
;   {
;   const int lane = tid & 63, w = tid >> 6, r = lane & 15, g = lane >> 4, wm = w >> 2, wn = w & 3;
;   __syncthreads();
;   GLOAD(Ag, Bg, 64)
;   __builtin_amdgcn_sched_barrier(0);
;   GCOMPUTE_KS(As0, Bs0, 0)
;   __builtin_amdgcn_sched_barrier(0);
;   GSTORE(As1, Bs1)
;   GLOAD(Ag, Bg, 128)
;   __builtin_amdgcn_sched_barrier(0);
;   GCOMPUTE_KS(As0, Bs0, 1)
;   __builtin_amdgcn_sched_barrier(0);
.LBB0_69:
	v_lshl_add_u64 v[94:95], s[48:49], 0, v[196:197]
	v_add_co_u32_e32 v96, vcc, s33, v94
	v_lshl_add_u64 v[102:103], s[46:47], 0, v[196:197]
	s_nop 0
	v_addc_co_u32_e32 v97, vcc, 0, v95, vcc
	v_add_co_u32_e32 v98, vcc, s35, v94
	s_waitcnt lgkmcnt(0)
	s_nop 0
	v_addc_co_u32_e32 v99, vcc, 0, v95, vcc
	v_add_co_u32_e32 v100, vcc, s39, v94
	s_barrier
	s_nop 0
	v_addc_co_u32_e32 v101, vcc, 0, v95, vcc
	v_add_co_u32_e32 v104, vcc, s33, v102
	s_nop 1
	v_addc_co_u32_e32 v105, vcc, 0, v103, vcc
	v_add_co_u32_e32 v106, vcc, s35, v102
	global_load_dwordx4 v[2:5], v[94:95], off offset:128
	global_load_dwordx4 v[6:9], v[96:97], off offset:128
	v_addc_co_u32_e32 v107, vcc, 0, v103, vcc
	v_add_co_u32_e32 v110, vcc, s39, v102
	global_load_dwordx4 v[10:13], v[98:99], off offset:128
	global_load_dwordx4 v[14:17], v[100:101], off offset:128
	global_load_dwordx4 v[18:21], v[102:103], off offset:128
	global_load_dwordx4 v[22:25], v[104:105], off offset:128
	v_addc_co_u32_e32 v111, vcc, 0, v103, vcc
	global_load_dwordx4 v[26:29], v[106:107], off offset:128
	global_load_dwordx4 v[30:33], v[110:111], off offset:128
	s_movk_i32 s99, 13
	s_mov_b32 s34, 0x3fb504f3
	s_mov_b64 s[100:101], s[18:19]
	s_mov_b32 s98, 0
	s_cmp_lg_u32 s50, 0
	s_cbranch_scc1 .Lsplitk_std
	s_cmp_lg_u32 s56, 2
	s_cbranch_scc1 .Lsplitk_cur_done
	s_movk_i32 s99, 5
	s_cmp_lt_u32 s84, 8
	s_cbranch_scc1 .Lsplitk_cur_done
	s_mov_b32 s34, 0
	v_readlane_b32 s2, v254, 11
	s_lshl_b32 s2, s2, 24
	s_sub_u32 s2, 0x8000000, s2
	s_add_u32 s100, s100, s2
	s_addc_u32 s101, s101, 0
.Lsplitk_cur_done:
	s_add_i32 s56, s56, 1
	s_cmp_lg_u32 s56, 2
	s_cbranch_scc1 .Lsplitk_std2
	s_movk_i32 s2, 0x3e8
	s_cmp_ge_u32 s84, 16
	s_cbranch_scc1 .Lsplitk_sched
	s_and_b32 s2, s84, 7
	s_add_i32 s2, s2, 64
	s_lshr_b32 s98, s84, 3
	s_lshl_b32 s98, s98, 10
	s_branch .Lsplitk_sched
.Lsplitk_std:
	s_add_i32 s56, s56, 1
.Lsplitk_std2:
	s_mul_i32 s2, s56, s57
	s_add_i32 s2, s2, s84
.Lsplitk_sched:
	s_cmp_ge_u32 s2, s25
	s_cselect_b64 s[40:41], -1, 0
	s_lshr_b32 s42, s2, 2
	s_add_i32 s42, s42, s51
	s_lshl_b32 s58, s42, 8
	s_lshl_b32 s42, s2, 8
	s_and_b32 s59, s42, 0x300
	s_lshl_b32 s42, s59, 11
	s_cmp_lt_u32 s2, s25
	s_cselect_b32 s2, s58, 0
	s_cselect_b32 s44, s42, 0
	s_lshl_b64 s[42:43], s[2:3], 11
	s_add_u32 s42, s16, s42
	s_mov_b32 s64, 1
	s_addc_u32 s43, s17, s43
	s_add_u32 s42, s42, s98
	s_addc_u32 s43, s43, 0
	ds_read_b128 v[34:37], v227
	ds_read_b128 v[38:41], v207 offset:32768
	ds_read_b128 v[42:45], v207 offset:34816
	ds_read_b128 v[46:49], v227 offset:2048
	ds_read_b128 v[58:61], v207 offset:36864
	ds_read_b128 v[62:65], v207 offset:38912
	ds_read_b128 v[82:85], v227 offset:4096
	ds_read_b128 v[86:89], v227 offset:6144
	s_waitcnt lgkmcnt(6)
	v_mfma_f32_16x16x32_bf16 v[50:53], v[34:37], v[38:41], 0
	s_add_u32 s44, s26, s44
	s_addc_u32 s45, s27, 0
	s_add_u32 s44, s44, s98
	s_addc_u32 s45, s45, 0
	s_waitcnt lgkmcnt(0)
	v_mfma_f32_16x16x32_bf16 v[126:129], v[86:89], v[38:41], 0
	v_mfma_f32_16x16x32_bf16 v[130:133], v[86:89], v[42:45], 0
	v_mfma_f32_16x16x32_bf16 v[134:137], v[86:89], v[58:61], 0
	v_mfma_f32_16x16x32_bf16 v[138:141], v[86:89], v[62:65], 0
	ds_read_b128 v[86:89], v227 offset:8192
	ds_read_b128 v[90:93], v227 offset:10240
	s_waitcnt lgkmcnt(1)
	v_mfma_f32_16x16x32_bf16 v[142:145], v[86:89], v[38:41], 0
	v_mfma_f32_16x16x32_bf16 v[146:149], v[86:89], v[42:45], 0
	v_mfma_f32_16x16x32_bf16 v[150:153], v[86:89], v[58:61], 0
	v_mfma_f32_16x16x32_bf16 v[154:157], v[86:89], v[62:65], 0
	s_waitcnt lgkmcnt(0)
	v_mfma_f32_16x16x32_bf16 v[158:161], v[90:93], v[38:41], 0
	v_mfma_f32_16x16x32_bf16 v[162:165], v[90:93], v[42:45], 0
	v_mfma_f32_16x16x32_bf16 v[166:169], v[90:93], v[58:61], 0
	v_mfma_f32_16x16x32_bf16 v[170:173], v[90:93], v[62:65], 0
	ds_read_b128 v[86:89], v227 offset:12288
	ds_read_b128 v[90:93], v227 offset:14336
	v_mfma_f32_16x16x32_bf16 v[54:57], v[34:37], v[42:45], 0
	v_mfma_f32_16x16x32_bf16 v[66:69], v[34:37], v[58:61], 0
	v_mfma_f32_16x16x32_bf16 v[34:37], v[34:37], v[62:65], 0
	v_mfma_f32_16x16x32_bf16 v[70:73], v[46:49], v[38:41], 0
	v_mfma_f32_16x16x32_bf16 v[74:77], v[46:49], v[42:45], 0
	v_mfma_f32_16x16x32_bf16 v[78:81], v[46:49], v[58:61], 0
	v_mfma_f32_16x16x32_bf16 v[46:49], v[46:49], v[62:65], 0
	v_mfma_f32_16x16x32_bf16 v[114:117], v[82:85], v[38:41], 0
	v_mfma_f32_16x16x32_bf16 v[118:121], v[82:85], v[42:45], 0
	v_mfma_f32_16x16x32_bf16 v[122:125], v[82:85], v[58:61], 0
	v_mfma_f32_16x16x32_bf16 v[82:85], v[82:85], v[62:65], 0
	s_waitcnt lgkmcnt(1)
	v_mfma_f32_16x16x32_bf16 v[174:177], v[86:89], v[38:41], 0
	v_mfma_f32_16x16x32_bf16 v[178:181], v[86:89], v[42:45], 0
	v_mfma_f32_16x16x32_bf16 v[182:185], v[86:89], v[58:61], 0
	v_mfma_f32_16x16x32_bf16 v[186:189], v[86:89], v[62:65], 0
	s_waitcnt lgkmcnt(0)
	v_mfma_f32_16x16x32_bf16 v[190:193], v[90:93], v[38:41], 0
	v_mfma_f32_16x16x32_bf16 v[212:215], v[90:93], v[42:45], 0
	v_mfma_f32_16x16x32_bf16 v[216:219], v[90:93], v[58:61], 0
	v_mfma_f32_16x16x32_bf16 v[220:223], v[90:93], v[62:65], 0
	s_waitcnt vmcnt(7)
	ds_write_b128 v199, v[2:5]
	s_waitcnt vmcnt(6)
	ds_write_b128 v200, v[6:9]
	s_waitcnt vmcnt(5)
	ds_write_b128 v201, v[10:13]
	s_waitcnt vmcnt(4)
	ds_write_b128 v202, v[14:17]
	s_waitcnt vmcnt(3)
	ds_write_b128 v203, v[18:21]
	s_waitcnt vmcnt(2)
	ds_write_b128 v204, v[22:25]
	s_waitcnt vmcnt(1)
	ds_write_b128 v205, v[26:29]
	s_waitcnt vmcnt(0)
; #define GCOMPUTE(AS, BS) GCOMPUTE_KS(AS, BS, 0) GCOMPUTE_KS(AS, BS, 1)
; template <int EPI>
; DI void gemm_phase(const P& p, int l, const u16* __restrict__ A, const u16* __restrict__ Bt, int mpx, char* lds) {
;     ...
;   GSTORE(As1, Bs1)
;   GLOAD(Ag, Bg, 128)
;   __builtin_amdgcn_sched_barrier(0);
;   GCOMPUTE_KS(As0, Bs0, 1)
;   __builtin_amdgcn_sched_barrier(0);
; #pragma unroll 1
;   for (int kk = 1; kk < 15; kk += 2) {
;     __syncthreads();
;     GSTORE(As0, Bs0)
;     GLOAD(Ag, Bg, (kk + 2) * 64)
;     __builtin_amdgcn_sched_barrier(0);
;     GCOMPUTE(As1, Bs1)
	ds_write_b128 v206, v[30:33]
	global_load_dwordx4 v[18:21], v[94:95], off offset:256
	global_load_dwordx4 v[86:89], v[96:97], off offset:256
	global_load_dwordx4 v[90:93], v[98:99], off offset:256
	s_nop 0
	global_load_dwordx4 v[94:97], v[100:101], off offset:256
	s_nop 0
	global_load_dwordx4 v[98:101], v[102:103], off offset:256
	s_nop 0
	global_load_dwordx4 v[102:105], v[104:105], off offset:256
	s_nop 0
	global_load_dwordx4 v[106:109], v[106:107], off offset:256
	s_nop 0
	global_load_dwordx4 v[110:113], v[110:111], off offset:256
	ds_read_b128 v[2:5], v229
	ds_read_b128 v[234:237], v228 offset:32768
	ds_read_b128 v[238:241], v228 offset:34816
	ds_read_b128 v[242:245], v228 offset:36864
	ds_read_b128 v[246:249], v228 offset:38912
	s_waitcnt lgkmcnt(3)
	v_mfma_f32_16x16x32_bf16 v[6:9], v[2:5], v[234:237], v[50:53]
	s_waitcnt lgkmcnt(2)
	v_mfma_f32_16x16x32_bf16 v[10:13], v[2:5], v[238:241], v[54:57]
	s_waitcnt lgkmcnt(1)
	v_mfma_f32_16x16x32_bf16 v[14:17], v[2:5], v[242:245], v[66:69]
	s_waitcnt lgkmcnt(0)
	v_mfma_f32_16x16x32_bf16 v[22:25], v[2:5], v[246:249], v[34:37]
	ds_read_b128 v[2:5], v229 offset:2048
	s_waitcnt lgkmcnt(0)
	v_mfma_f32_16x16x32_bf16 v[26:29], v[2:5], v[234:237], v[70:73]
	v_mfma_f32_16x16x32_bf16 v[30:33], v[2:5], v[238:241], v[74:77]
	v_mfma_f32_16x16x32_bf16 v[34:37], v[2:5], v[242:245], v[78:81]
	v_mfma_f32_16x16x32_bf16 v[38:41], v[2:5], v[246:249], v[46:49]
	ds_read_b128 v[2:5], v229 offset:4096
	s_waitcnt lgkmcnt(0)
	v_mfma_f32_16x16x32_bf16 v[42:45], v[2:5], v[234:237], v[114:117]
	v_mfma_f32_16x16x32_bf16 v[46:49], v[2:5], v[238:241], v[118:121]
	v_mfma_f32_16x16x32_bf16 v[50:53], v[2:5], v[242:245], v[122:125]
	v_mfma_f32_16x16x32_bf16 v[54:57], v[2:5], v[246:249], v[82:85]
	ds_read_b128 v[2:5], v229 offset:6144
	s_waitcnt lgkmcnt(0)
	v_mfma_f32_16x16x32_bf16 v[58:61], v[2:5], v[234:237], v[126:129]
	v_mfma_f32_16x16x32_bf16 v[62:65], v[2:5], v[238:241], v[130:133]
	v_mfma_f32_16x16x32_bf16 v[66:69], v[2:5], v[242:245], v[134:137]
	v_mfma_f32_16x16x32_bf16 v[70:73], v[2:5], v[246:249], v[138:141]
	ds_read_b128 v[2:5], v229 offset:8192
	s_waitcnt lgkmcnt(0)
	v_mfma_f32_16x16x32_bf16 v[74:77], v[2:5], v[234:237], v[142:145]
	v_mfma_f32_16x16x32_bf16 v[78:81], v[2:5], v[238:241], v[146:149]
	v_mfma_f32_16x16x32_bf16 v[82:85], v[2:5], v[242:245], v[150:153]
	v_mfma_f32_16x16x32_bf16 v[114:117], v[2:5], v[246:249], v[154:157]
	ds_read_b128 v[2:5], v229 offset:10240
	s_waitcnt lgkmcnt(0)
	v_mfma_f32_16x16x32_bf16 v[118:121], v[2:5], v[234:237], v[158:161]
	v_mfma_f32_16x16x32_bf16 v[122:125], v[2:5], v[238:241], v[162:165]
	v_mfma_f32_16x16x32_bf16 v[126:129], v[2:5], v[242:245], v[166:169]
	v_mfma_f32_16x16x32_bf16 v[130:133], v[2:5], v[246:249], v[170:173]
	ds_read_b128 v[2:5], v229 offset:12288
	s_waitcnt lgkmcnt(0)
	v_mfma_f32_16x16x32_bf16 v[134:137], v[2:5], v[234:237], v[174:177]
	v_mfma_f32_16x16x32_bf16 v[138:141], v[2:5], v[238:241], v[178:181]
	v_mfma_f32_16x16x32_bf16 v[142:145], v[2:5], v[242:245], v[182:185]
	v_mfma_f32_16x16x32_bf16 v[146:149], v[2:5], v[246:249], v[186:189]
	ds_read_b128 v[2:5], v229 offset:14336
	s_waitcnt lgkmcnt(0)
	v_mfma_f32_16x16x32_bf16 v[150:153], v[2:5], v[234:237], v[190:193]
	v_mfma_f32_16x16x32_bf16 v[154:157], v[2:5], v[238:241], v[212:215]
	v_mfma_f32_16x16x32_bf16 v[158:161], v[2:5], v[242:245], v[216:219]
	v_mfma_f32_16x16x32_bf16 v[2:5], v[2:5], v[246:249], v[220:223]
	s_movk_i32 s62, 0x100
	s_mov_b64 s[52:53], s[46:47]
	s_mov_b64 s[54:55], s[48:49]
	v_add_u32_e32 v208, s33, v196
	v_add_u32_e32 v209, s35, v196
	v_add_u32_e32 v210, s39, v196
	s_barrier
	ds_read_b128 v[212:215], v230
	ds_read_b128 v[216:219], v230 offset:2048
	ds_read_b128 v[220:223], v230 offset:4096
	ds_read_b128 v[234:237], v230 offset:6144
	ds_read_b128 v[238:241], v231
	ds_read_b128 v[242:245], v231 offset:2048
	ds_read_b128 v[246:249], v231 offset:4096
	ds_read_b128 v[250:253], v231 offset:6144
.LBB0_70:
	s_add_i32 s63, s64, 2
	s_waitcnt lgkmcnt(3)
	v_mfma_f32_16x16x32_bf16 v[6:9], v[238:241], v[212:215], v[6:9]
	v_mfma_f32_16x16x32_bf16 v[10:13], v[238:241], v[216:219], v[10:13]
	v_mfma_f32_16x16x32_bf16 v[14:17], v[238:241], v[220:223], v[14:17]
	v_mfma_f32_16x16x32_bf16 v[22:25], v[238:241], v[234:237], v[22:25]
	ds_read_b128 v[238:241], v231 offset:8192
	global_load_dwordx4 v[162:165], v196, s[54:55] offset:384
	s_waitcnt vmcnt(8)
	ds_write_b128 v198, v[18:21]
	s_waitcnt lgkmcnt(4)
	v_mfma_f32_16x16x32_bf16 v[26:29], v[242:245], v[212:215], v[26:29]
	v_mfma_f32_16x16x32_bf16 v[30:33], v[242:245], v[216:219], v[30:33]
	v_mfma_f32_16x16x32_bf16 v[34:37], v[242:245], v[220:223], v[34:37]
	v_mfma_f32_16x16x32_bf16 v[38:41], v[242:245], v[234:237], v[38:41]
	ds_read_b128 v[242:245], v231 offset:10240
	global_load_dwordx4 v[166:169], v208, s[54:55] offset:384
	s_waitcnt vmcnt(8)
	ds_write_b128 v198, v[86:89] offset:8192
	ds_read_b128 v[18:21], v232
	s_waitcnt lgkmcnt(6)
	v_mfma_f32_16x16x32_bf16 v[42:45], v[246:249], v[212:215], v[42:45]
	v_mfma_f32_16x16x32_bf16 v[46:49], v[246:249], v[216:219], v[46:49]
	v_mfma_f32_16x16x32_bf16 v[50:53], v[246:249], v[220:223], v[50:53]
	v_mfma_f32_16x16x32_bf16 v[54:57], v[246:249], v[234:237], v[54:57]
	ds_read_b128 v[246:249], v231 offset:12288
	global_load_dwordx4 v[170:173], v209, s[54:55] offset:384
	s_waitcnt vmcnt(8)
	ds_write_b128 v198, v[90:93] offset:16384
	ds_read_b128 v[86:89], v232 offset:2048
	s_waitcnt lgkmcnt(8)
	v_mfma_f32_16x16x32_bf16 v[58:61], v[250:253], v[212:215], v[58:61]
	v_mfma_f32_16x16x32_bf16 v[62:65], v[250:253], v[216:219], v[62:65]
	v_mfma_f32_16x16x32_bf16 v[66:69], v[250:253], v[220:223], v[66:69]
	v_mfma_f32_16x16x32_bf16 v[70:73], v[250:253], v[234:237], v[70:73]
	ds_read_b128 v[250:253], v231 offset:14336
	global_load_dwordx4 v[174:177], v210, s[54:55] offset:384
	s_waitcnt vmcnt(8)
; #define GCOMPUTE(AS, BS) GCOMPUTE_KS(AS, BS, 0) GCOMPUTE_KS(AS, BS, 1)
; template <int EPI>
; DI void gemm_phase(const P& p, int l, const u16* __restrict__ A, const u16* __restrict__ Bt, int mpx, char* lds) {
;     ...
;   for (int kk = 1; kk < 15; kk += 2) {
;     __syncthreads();
;     GSTORE(As0, Bs0)
;     GLOAD(Ag, Bg, (kk + 2) * 64)
;     __builtin_amdgcn_sched_barrier(0);
;     GCOMPUTE(As1, Bs1)
;     __builtin_amdgcn_sched_barrier(0);
;     __syncthreads();
;     GSTORE(As1, Bs1)
;     {
;       const bool in_tile = kk + 3 < 16;
;       const u16* pa = in_tile ? Ag : Agn;
;       const u16* pb = in_tile ? Bg : Bgn;
;       const int k0 = in_tile ? (kk + 3) * 64 : 0;
;       GLOAD(pa, pb, k0)
;     }
;     __builtin_amdgcn_sched_barrier(0);
;     GCOMPUTE(As0, Bs0)
	ds_write_b128 v198, v[94:97] offset:24576
	ds_read_b128 v[90:93], v232 offset:4096
	s_waitcnt lgkmcnt(10)
	v_mfma_f32_16x16x32_bf16 v[74:77], v[238:241], v[212:215], v[74:77]
	v_mfma_f32_16x16x32_bf16 v[78:81], v[238:241], v[216:219], v[78:81]
	v_mfma_f32_16x16x32_bf16 v[82:85], v[238:241], v[220:223], v[82:85]
	v_mfma_f32_16x16x32_bf16 v[114:117], v[238:241], v[234:237], v[114:117]
	ds_read_b128 v[238:241], v233
	global_load_dwordx4 v[178:181], v196, s[52:53] offset:384
	s_waitcnt vmcnt(8)
	ds_write_b128 v198, v[98:101] offset:32768
	ds_read_b128 v[94:97], v232 offset:6144
	s_waitcnt lgkmcnt(11)
	v_mfma_f32_16x16x32_bf16 v[118:121], v[242:245], v[212:215], v[118:121]
	v_mfma_f32_16x16x32_bf16 v[122:125], v[242:245], v[216:219], v[122:125]
	v_mfma_f32_16x16x32_bf16 v[126:129], v[242:245], v[220:223], v[126:129]
	v_mfma_f32_16x16x32_bf16 v[130:133], v[242:245], v[234:237], v[130:133]
	ds_read_b128 v[242:245], v233 offset:2048
	global_load_dwordx4 v[182:185], v208, s[52:53] offset:384
	s_waitcnt vmcnt(8)
	ds_write_b128 v198, v[102:105] offset:40960
	s_waitcnt lgkmcnt(10)
	v_mfma_f32_16x16x32_bf16 v[134:137], v[246:249], v[212:215], v[134:137]
	v_mfma_f32_16x16x32_bf16 v[138:141], v[246:249], v[216:219], v[138:141]
	v_mfma_f32_16x16x32_bf16 v[142:145], v[246:249], v[220:223], v[142:145]
	v_mfma_f32_16x16x32_bf16 v[146:149], v[246:249], v[234:237], v[146:149]
	ds_read_b128 v[246:249], v233 offset:4096
	global_load_dwordx4 v[186:189], v209, s[52:53] offset:384
	s_waitcnt vmcnt(8)
	ds_write_b128 v198, v[106:109] offset:49152
	s_waitcnt lgkmcnt(9)
	v_mfma_f32_16x16x32_bf16 v[150:153], v[250:253], v[212:215], v[150:153]
	v_mfma_f32_16x16x32_bf16 v[154:157], v[250:253], v[216:219], v[154:157]
	v_mfma_f32_16x16x32_bf16 v[158:161], v[250:253], v[220:223], v[158:161]
	v_mfma_f32_16x16x32_bf16 v[2:5], v[250:253], v[234:237], v[2:5]
	ds_read_b128 v[250:253], v233 offset:6144
	global_load_dwordx4 v[190:193], v210, s[52:53] offset:384
	s_waitcnt vmcnt(8)
	ds_write_b128 v198, v[110:113] offset:57344
	s_waitcnt lgkmcnt(6)
	v_mfma_f32_16x16x32_bf16 v[6:9], v[238:241], v[18:21], v[6:9]
	v_mfma_f32_16x16x32_bf16 v[10:13], v[238:241], v[86:89], v[10:13]
	v_mfma_f32_16x16x32_bf16 v[14:17], v[238:241], v[90:93], v[14:17]
	v_mfma_f32_16x16x32_bf16 v[22:25], v[238:241], v[94:97], v[22:25]
	ds_read_b128 v[238:241], v233 offset:8192
	s_waitcnt lgkmcnt(6)
	v_mfma_f32_16x16x32_bf16 v[26:29], v[242:245], v[18:21], v[26:29]
	v_mfma_f32_16x16x32_bf16 v[30:33], v[242:245], v[86:89], v[30:33]
	v_mfma_f32_16x16x32_bf16 v[34:37], v[242:245], v[90:93], v[34:37]
	v_mfma_f32_16x16x32_bf16 v[38:41], v[242:245], v[94:97], v[38:41]
	ds_read_b128 v[242:245], v233 offset:10240
	s_waitcnt lgkmcnt(5)
	v_mfma_f32_16x16x32_bf16 v[42:45], v[246:249], v[18:21], v[42:45]
	v_mfma_f32_16x16x32_bf16 v[46:49], v[246:249], v[86:89], v[46:49]
	v_mfma_f32_16x16x32_bf16 v[50:53], v[246:249], v[90:93], v[50:53]
	v_mfma_f32_16x16x32_bf16 v[54:57], v[246:249], v[94:97], v[54:57]
	ds_read_b128 v[246:249], v233 offset:12288
	s_waitcnt lgkmcnt(4)
	v_mfma_f32_16x16x32_bf16 v[58:61], v[250:253], v[18:21], v[58:61]
	v_mfma_f32_16x16x32_bf16 v[62:65], v[250:253], v[86:89], v[62:65]
	v_mfma_f32_16x16x32_bf16 v[66:69], v[250:253], v[90:93], v[66:69]
	v_mfma_f32_16x16x32_bf16 v[70:73], v[250:253], v[94:97], v[70:73]
	ds_read_b128 v[250:253], v233 offset:14336
	s_waitcnt lgkmcnt(3)
	v_mfma_f32_16x16x32_bf16 v[74:77], v[238:241], v[18:21], v[74:77]
	v_mfma_f32_16x16x32_bf16 v[78:81], v[238:241], v[86:89], v[78:81]
	v_mfma_f32_16x16x32_bf16 v[82:85], v[238:241], v[90:93], v[82:85]
	v_mfma_f32_16x16x32_bf16 v[114:117], v[238:241], v[94:97], v[114:117]
	s_waitcnt lgkmcnt(2)
	v_mfma_f32_16x16x32_bf16 v[118:121], v[242:245], v[18:21], v[118:121]
	v_mfma_f32_16x16x32_bf16 v[122:125], v[242:245], v[86:89], v[122:125]
	v_mfma_f32_16x16x32_bf16 v[126:129], v[242:245], v[90:93], v[126:129]
	v_mfma_f32_16x16x32_bf16 v[130:133], v[242:245], v[94:97], v[130:133]
	s_waitcnt lgkmcnt(0)
	s_cmp_lt_u32 s64, s99
	s_cselect_b64 s[66:67], -1, 0
	s_and_b64 s[66:67], s[66:67], exec
	s_cselect_b32 s2, s62, 0
	s_cselect_b32 s65, s49, s43
	s_cselect_b32 s68, s48, s42
	s_cselect_b32 s70, s47, s45
	s_cselect_b32 s71, s46, s44
	s_lshl_b64 s[66:67], s[2:3], 1
	s_add_u32 s68, s68, s66
	s_addc_u32 s69, s65, s67
	s_add_u32 s66, s71, s66
	s_addc_u32 s67, s70, s67
	s_barrier
; #define GCOMPUTE(AS, BS) GCOMPUTE_KS(AS, BS, 0) GCOMPUTE_KS(AS, BS, 1)
; template <int EPI>
; DI void gemm_phase(const P& p, int l, const u16* __restrict__ A, const u16* __restrict__ Bt, int mpx, char* lds) {
;     ...
;     __syncthreads();
;     GSTORE(As1, Bs1)
;     {
;       const bool in_tile = kk + 3 < 16;
;       const u16* pa = in_tile ? Ag : Agn;
;       const u16* pb = in_tile ? Bg : Bgn;
;       const int k0 = in_tile ? (kk + 3) * 64 : 0;
;       GLOAD(pa, pb, k0)
;     }
;     __builtin_amdgcn_sched_barrier(0);
;     GCOMPUTE(As0, Bs0)
;     __builtin_amdgcn_sched_barrier(0);
;   }
	ds_read_b128 v[212:215], v207 offset:32768
	ds_read_b128 v[216:219], v207 offset:34816
	ds_read_b128 v[220:223], v207 offset:36864
	ds_read_b128 v[234:237], v207 offset:38912
	ds_read_b128 v[238:241], v227
	ds_read_b128 v[242:245], v227 offset:2048
	v_mfma_f32_16x16x32_bf16 v[134:137], v[246:249], v[18:21], v[134:137]
	v_mfma_f32_16x16x32_bf16 v[138:141], v[246:249], v[86:89], v[138:141]
	v_mfma_f32_16x16x32_bf16 v[142:145], v[246:249], v[90:93], v[142:145]
	v_mfma_f32_16x16x32_bf16 v[146:149], v[246:249], v[94:97], v[146:149]
	ds_read_b128 v[246:249], v227 offset:4096
	v_mfma_f32_16x16x32_bf16 v[150:153], v[250:253], v[18:21], v[150:153]
	v_mfma_f32_16x16x32_bf16 v[154:157], v[250:253], v[86:89], v[154:157]
	v_mfma_f32_16x16x32_bf16 v[158:161], v[250:253], v[90:93], v[158:161]
	v_mfma_f32_16x16x32_bf16 v[2:5], v[250:253], v[94:97], v[2:5]
	ds_read_b128 v[250:253], v227 offset:6144
	s_waitcnt lgkmcnt(3)
	v_mfma_f32_16x16x32_bf16 v[6:9], v[238:241], v[212:215], v[6:9]
	v_mfma_f32_16x16x32_bf16 v[10:13], v[238:241], v[216:219], v[10:13]
	v_mfma_f32_16x16x32_bf16 v[14:17], v[238:241], v[220:223], v[14:17]
	v_mfma_f32_16x16x32_bf16 v[22:25], v[238:241], v[234:237], v[22:25]
	ds_read_b128 v[238:241], v227 offset:8192
	global_load_dwordx4 v[18:21], v196, s[68:69]
	s_waitcnt vmcnt(8)
	ds_write_b128 v199, v[162:165]
	s_waitcnt lgkmcnt(4)
	v_mfma_f32_16x16x32_bf16 v[26:29], v[242:245], v[212:215], v[26:29]
	v_mfma_f32_16x16x32_bf16 v[30:33], v[242:245], v[216:219], v[30:33]
	v_mfma_f32_16x16x32_bf16 v[34:37], v[242:245], v[220:223], v[34:37]
	v_mfma_f32_16x16x32_bf16 v[38:41], v[242:245], v[234:237], v[38:41]
	ds_read_b128 v[242:245], v227 offset:10240
	global_load_dwordx4 v[86:89], v208, s[68:69]
	s_waitcnt vmcnt(8)
	ds_write_b128 v200, v[166:169]
	ds_read_b128 v[162:165], v228 offset:32768
	s_waitcnt lgkmcnt(6)
	v_mfma_f32_16x16x32_bf16 v[42:45], v[246:249], v[212:215], v[42:45]
	v_mfma_f32_16x16x32_bf16 v[46:49], v[246:249], v[216:219], v[46:49]
	v_mfma_f32_16x16x32_bf16 v[50:53], v[246:249], v[220:223], v[50:53]
	v_mfma_f32_16x16x32_bf16 v[54:57], v[246:249], v[234:237], v[54:57]
	ds_read_b128 v[246:249], v227 offset:12288
	global_load_dwordx4 v[90:93], v209, s[68:69]
	s_waitcnt vmcnt(8)
	ds_write_b128 v201, v[170:173]
	ds_read_b128 v[166:169], v228 offset:34816
	s_waitcnt lgkmcnt(8)
	v_mfma_f32_16x16x32_bf16 v[58:61], v[250:253], v[212:215], v[58:61]
	v_mfma_f32_16x16x32_bf16 v[62:65], v[250:253], v[216:219], v[62:65]
	v_mfma_f32_16x16x32_bf16 v[66:69], v[250:253], v[220:223], v[66:69]
	v_mfma_f32_16x16x32_bf16 v[70:73], v[250:253], v[234:237], v[70:73]
	ds_read_b128 v[250:253], v227 offset:14336
	global_load_dwordx4 v[94:97], v210, s[68:69]
	s_waitcnt vmcnt(8)
	ds_write_b128 v202, v[174:177]
	ds_read_b128 v[170:173], v228 offset:36864
	s_waitcnt lgkmcnt(10)
	v_mfma_f32_16x16x32_bf16 v[74:77], v[238:241], v[212:215], v[74:77]
	v_mfma_f32_16x16x32_bf16 v[78:81], v[238:241], v[216:219], v[78:81]
	v_mfma_f32_16x16x32_bf16 v[82:85], v[238:241], v[220:223], v[82:85]
	v_mfma_f32_16x16x32_bf16 v[114:117], v[238:241], v[234:237], v[114:117]
	ds_read_b128 v[238:241], v229
	global_load_dwordx4 v[98:101], v196, s[66:67]
	s_waitcnt vmcnt(8)
	ds_write_b128 v203, v[178:181]
	ds_read_b128 v[174:177], v228 offset:38912
	s_waitcnt lgkmcnt(11)
	v_mfma_f32_16x16x32_bf16 v[118:121], v[242:245], v[212:215], v[118:121]
	v_mfma_f32_16x16x32_bf16 v[122:125], v[242:245], v[216:219], v[122:125]
	v_mfma_f32_16x16x32_bf16 v[126:129], v[242:245], v[220:223], v[126:129]
	v_mfma_f32_16x16x32_bf16 v[130:133], v[242:245], v[234:237], v[130:133]
	ds_read_b128 v[242:245], v229 offset:2048
	global_load_dwordx4 v[102:105], v208, s[66:67]
	s_waitcnt vmcnt(8)
	ds_write_b128 v204, v[182:185]
	s_waitcnt lgkmcnt(10)
	v_mfma_f32_16x16x32_bf16 v[134:137], v[246:249], v[212:215], v[134:137]
	v_mfma_f32_16x16x32_bf16 v[138:141], v[246:249], v[216:219], v[138:141]
	v_mfma_f32_16x16x32_bf16 v[142:145], v[246:249], v[220:223], v[142:145]
	v_mfma_f32_16x16x32_bf16 v[146:149], v[246:249], v[234:237], v[146:149]
	ds_read_b128 v[246:249], v229 offset:4096
	global_load_dwordx4 v[106:109], v209, s[66:67]
	s_waitcnt vmcnt(8)
	ds_write_b128 v205, v[186:189]
	s_waitcnt lgkmcnt(9)
	v_mfma_f32_16x16x32_bf16 v[150:153], v[250:253], v[212:215], v[150:153]
	v_mfma_f32_16x16x32_bf16 v[154:157], v[250:253], v[216:219], v[154:157]
	v_mfma_f32_16x16x32_bf16 v[158:161], v[250:253], v[220:223], v[158:161]
	v_mfma_f32_16x16x32_bf16 v[2:5], v[250:253], v[234:237], v[2:5]
	ds_read_b128 v[250:253], v229 offset:6144
	global_load_dwordx4 v[110:113], v210, s[66:67]
	s_waitcnt vmcnt(8)
	ds_write_b128 v206, v[190:193]
	s_waitcnt lgkmcnt(6)
	v_mfma_f32_16x16x32_bf16 v[6:9], v[238:241], v[162:165], v[6:9]
	v_mfma_f32_16x16x32_bf16 v[10:13], v[238:241], v[166:169], v[10:13]
	v_mfma_f32_16x16x32_bf16 v[14:17], v[238:241], v[170:173], v[14:17]
	v_mfma_f32_16x16x32_bf16 v[22:25], v[238:241], v[174:177], v[22:25]
	ds_read_b128 v[238:241], v229 offset:8192
	s_waitcnt lgkmcnt(6)
	v_mfma_f32_16x16x32_bf16 v[26:29], v[242:245], v[162:165], v[26:29]
	v_mfma_f32_16x16x32_bf16 v[30:33], v[242:245], v[166:169], v[30:33]
	v_mfma_f32_16x16x32_bf16 v[34:37], v[242:245], v[170:173], v[34:37]
	v_mfma_f32_16x16x32_bf16 v[38:41], v[242:245], v[174:177], v[38:41]
	ds_read_b128 v[242:245], v229 offset:10240
	s_waitcnt lgkmcnt(5)
	v_mfma_f32_16x16x32_bf16 v[42:45], v[246:249], v[162:165], v[42:45]
	v_mfma_f32_16x16x32_bf16 v[46:49], v[246:249], v[166:169], v[46:49]
	v_mfma_f32_16x16x32_bf16 v[50:53], v[246:249], v[170:173], v[50:53]
	v_mfma_f32_16x16x32_bf16 v[54:57], v[246:249], v[174:177], v[54:57]
	ds_read_b128 v[246:249], v229 offset:12288
	s_waitcnt lgkmcnt(4)
	v_mfma_f32_16x16x32_bf16 v[58:61], v[250:253], v[162:165], v[58:61]
	v_mfma_f32_16x16x32_bf16 v[62:65], v[250:253], v[166:169], v[62:65]
	v_mfma_f32_16x16x32_bf16 v[66:69], v[250:253], v[170:173], v[66:69]
	v_mfma_f32_16x16x32_bf16 v[70:73], v[250:253], v[174:177], v[70:73]
	ds_read_b128 v[250:253], v229 offset:14336
	s_waitcnt lgkmcnt(3)
	v_mfma_f32_16x16x32_bf16 v[74:77], v[238:241], v[162:165], v[74:77]
	v_mfma_f32_16x16x32_bf16 v[78:81], v[238:241], v[166:169], v[78:81]
	v_mfma_f32_16x16x32_bf16 v[82:85], v[238:241], v[170:173], v[82:85]
	v_mfma_f32_16x16x32_bf16 v[114:117], v[238:241], v[174:177], v[114:117]
	s_waitcnt lgkmcnt(2)
	v_mfma_f32_16x16x32_bf16 v[118:121], v[242:245], v[162:165], v[118:121]
	v_mfma_f32_16x16x32_bf16 v[122:125], v[242:245], v[166:169], v[122:125]
	v_mfma_f32_16x16x32_bf16 v[126:129], v[242:245], v[170:173], v[126:129]
	v_mfma_f32_16x16x32_bf16 v[130:133], v[242:245], v[174:177], v[130:133]
	s_waitcnt lgkmcnt(0)
	s_addk_i32 s62, 0x80
	s_add_u32 s54, s54, 0x100
	s_addc_u32 s55, s55, 0
	s_add_u32 s52, s52, 0x100
	s_addc_u32 s53, s53, 0
	s_cmp_ge_u32 s64, s99
	s_mov_b32 s64, s63
	s_cbranch_scc1 .Lgemm_out_exit
; #define GCOMPUTE(AS, BS) GCOMPUTE_KS(AS, BS, 0) GCOMPUTE_KS(AS, BS, 1)
; template <int EPI>
; DI void gemm_phase(const P& p, int l, const u16* __restrict__ A, const u16* __restrict__ Bt, int mpx, char* lds) {
;     ...
;     GCOMPUTE(As0, Bs0)
;     __builtin_amdgcn_sched_barrier(0);
;   }
;   __syncthreads();
;   __builtin_amdgcn_sched_barrier(0);
;   GCOMPUTE(As1, Bs1)
;   __builtin_amdgcn_sched_barrier(0);
	s_barrier
	ds_read_b128 v[212:215], v230
	ds_read_b128 v[216:219], v230 offset:2048
	ds_read_b128 v[220:223], v230 offset:4096
	ds_read_b128 v[234:237], v230 offset:6144
	ds_read_b128 v[238:241], v231
	ds_read_b128 v[242:245], v231 offset:2048
	v_mfma_f32_16x16x32_bf16 v[134:137], v[246:249], v[162:165], v[134:137]
	v_mfma_f32_16x16x32_bf16 v[138:141], v[246:249], v[166:169], v[138:141]
	v_mfma_f32_16x16x32_bf16 v[142:145], v[246:249], v[170:173], v[142:145]
	v_mfma_f32_16x16x32_bf16 v[146:149], v[246:249], v[174:177], v[146:149]
	ds_read_b128 v[246:249], v231 offset:4096
	v_mfma_f32_16x16x32_bf16 v[150:153], v[250:253], v[162:165], v[150:153]
	v_mfma_f32_16x16x32_bf16 v[154:157], v[250:253], v[166:169], v[154:157]
	v_mfma_f32_16x16x32_bf16 v[158:161], v[250:253], v[170:173], v[158:161]
	v_mfma_f32_16x16x32_bf16 v[2:5], v[250:253], v[174:177], v[2:5]
	ds_read_b128 v[250:253], v231 offset:6144
	s_branch .LBB0_70
.Lgemm_out_exit:
	v_mfma_f32_16x16x32_bf16 v[134:137], v[246:249], v[162:165], v[134:137]
	v_mfma_f32_16x16x32_bf16 v[138:141], v[246:249], v[166:169], v[138:141]
	v_mfma_f32_16x16x32_bf16 v[142:145], v[246:249], v[170:173], v[142:145]
	v_mfma_f32_16x16x32_bf16 v[146:149], v[246:249], v[174:177], v[146:149]
	v_mfma_f32_16x16x32_bf16 v[150:153], v[250:253], v[162:165], v[150:153]
	v_mfma_f32_16x16x32_bf16 v[154:157], v[250:253], v[166:169], v[154:157]
	v_mfma_f32_16x16x32_bf16 v[158:161], v[250:253], v[170:173], v[158:161]
	v_mfma_f32_16x16x32_bf16 v[2:5], v[250:253], v[174:177], v[2:5]
	s_barrier
	ds_read_b128 v[162:165], v231
	ds_read_b128 v[166:169], v230
	ds_read_b128 v[170:173], v230 offset:2048
	ds_read_b128 v[174:177], v230 offset:4096
	ds_read_b128 v[178:181], v230 offset:6144
	s_waitcnt lgkmcnt(3)
	v_mfma_f32_16x16x32_bf16 v[6:9], v[162:165], v[166:169], v[6:9]
	s_waitcnt lgkmcnt(2)
	v_mfma_f32_16x16x32_bf16 v[10:13], v[162:165], v[170:173], v[10:13]
	s_waitcnt lgkmcnt(1)
	v_mfma_f32_16x16x32_bf16 v[14:17], v[162:165], v[174:177], v[14:17]
	s_waitcnt lgkmcnt(0)
	v_mfma_f32_16x16x32_bf16 v[22:25], v[162:165], v[178:181], v[22:25]
	ds_read_b128 v[162:165], v231 offset:2048
	s_waitcnt lgkmcnt(0)
	v_mfma_f32_16x16x32_bf16 v[26:29], v[162:165], v[166:169], v[26:29]
	v_mfma_f32_16x16x32_bf16 v[30:33], v[162:165], v[170:173], v[30:33]
	v_mfma_f32_16x16x32_bf16 v[34:37], v[162:165], v[174:177], v[34:37]
	v_mfma_f32_16x16x32_bf16 v[38:41], v[162:165], v[178:181], v[38:41]
	ds_read_b128 v[162:165], v231 offset:4096
	s_waitcnt lgkmcnt(0)
	v_mfma_f32_16x16x32_bf16 v[42:45], v[162:165], v[166:169], v[42:45]
	v_mfma_f32_16x16x32_bf16 v[46:49], v[162:165], v[170:173], v[46:49]
	v_mfma_f32_16x16x32_bf16 v[50:53], v[162:165], v[174:177], v[50:53]
	v_mfma_f32_16x16x32_bf16 v[54:57], v[162:165], v[178:181], v[54:57]
	ds_read_b128 v[162:165], v231 offset:6144
	s_waitcnt lgkmcnt(0)
	v_mfma_f32_16x16x32_bf16 v[58:61], v[162:165], v[166:169], v[58:61]
	v_mfma_f32_16x16x32_bf16 v[62:65], v[162:165], v[170:173], v[62:65]
	v_mfma_f32_16x16x32_bf16 v[66:69], v[162:165], v[174:177], v[66:69]
	v_mfma_f32_16x16x32_bf16 v[162:165], v[162:165], v[178:181], v[70:73]
	s_nop 2
	ds_read_b128 v[70:73], v231 offset:8192
	s_waitcnt lgkmcnt(0)
	v_mfma_f32_16x16x32_bf16 v[182:185], v[70:73], v[166:169], v[74:77]
	s_nop 2
	ds_read_b128 v[74:77], v233
	v_mfma_f32_16x16x32_bf16 v[186:189], v[70:73], v[170:173], v[78:81]
	v_mfma_f32_16x16x32_bf16 v[190:193], v[70:73], v[174:177], v[82:85]
	v_mfma_f32_16x16x32_bf16 v[212:215], v[70:73], v[178:181], v[114:117]
	ds_read_b128 v[70:73], v231 offset:10240
	s_waitcnt lgkmcnt(0)
	v_mfma_f32_16x16x32_bf16 v[216:219], v[70:73], v[166:169], v[118:121]
	v_mfma_f32_16x16x32_bf16 v[220:223], v[70:73], v[170:173], v[122:125]
	v_mfma_f32_16x16x32_bf16 v[234:237], v[70:73], v[174:177], v[126:129]
	v_mfma_f32_16x16x32_bf16 v[238:241], v[70:73], v[178:181], v[130:133]
	ds_read_b128 v[70:73], v231 offset:12288
	s_waitcnt lgkmcnt(0)
	v_mfma_f32_16x16x32_bf16 v[242:245], v[70:73], v[166:169], v[134:137]
	v_mfma_f32_16x16x32_bf16 v[246:249], v[70:73], v[170:173], v[138:141]
	v_mfma_f32_16x16x32_bf16 v[250:253], v[70:73], v[174:177], v[142:145]
	v_mfma_f32_16x16x32_bf16 v[208:211], v[70:73], v[178:181], v[146:149]
	ds_read_b128 v[70:73], v231 offset:14336
	s_waitcnt lgkmcnt(0)
	v_mfma_f32_16x16x32_bf16 v[178:181], v[70:73], v[178:181], v[2:5]
	s_nop 2
	ds_read_b128 v[2:5], v232
	s_waitcnt lgkmcnt(0)
	v_mfma_f32_16x16x32_bf16 v[146:149], v[74:77], v[2:5], v[6:9]
	s_nop 2
	ds_read_b128 v[6:9], v232 offset:2048
	v_mfma_f32_16x16x32_bf16 v[170:173], v[70:73], v[170:173], v[154:157]
	s_waitcnt lgkmcnt(0)
	v_mfma_f32_16x16x32_bf16 v[154:157], v[74:77], v[6:9], v[10:13]
	s_nop 2
	ds_read_b128 v[10:13], v232 offset:4096
	v_mfma_f32_16x16x32_bf16 v[166:169], v[70:73], v[166:169], v[150:153]
	s_waitcnt lgkmcnt(0)
	v_mfma_f32_16x16x32_bf16 v[150:153], v[74:77], v[10:13], v[14:17]
	s_nop 2
	ds_read_b128 v[14:17], v232 offset:6144
	v_mfma_f32_16x16x32_bf16 v[174:177], v[70:73], v[174:177], v[158:161]
	s_waitcnt lgkmcnt(0)
	v_mfma_f32_16x16x32_bf16 v[158:161], v[74:77], v[14:17], v[22:25]
	s_nop 2
	ds_read_b128 v[22:25], v233 offset:2048
	s_waitcnt lgkmcnt(0)
	v_mfma_f32_16x16x32_bf16 v[138:141], v[22:25], v[2:5], v[26:29]
	s_nop 2
	ds_read_b128 v[26:29], v233 offset:12288
	v_mfma_f32_16x16x32_bf16 v[142:145], v[22:25], v[6:9], v[30:33]
	v_mfma_f32_16x16x32_bf16 v[130:133], v[22:25], v[10:13], v[34:37]
	v_mfma_f32_16x16x32_bf16 v[134:137], v[22:25], v[14:17], v[38:41]
	ds_read_b128 v[22:25], v233 offset:4096
	s_waitcnt lgkmcnt(0)
; #define GCOMPUTE(AS, BS) GCOMPUTE_KS(AS, BS, 0) GCOMPUTE_KS(AS, BS, 1)
; template <int EPI>
; DI void gemm_phase(const P& p, int l, const u16* __restrict__ A, const u16* __restrict__ Bt, int mpx, char* lds) {
;     ...
;   GCOMPUTE(As1, Bs1)
;   __builtin_amdgcn_sched_barrier(0);
;   }
;   __syncthreads();
;   GSTORE(As0, Bs0)
;     ...
;     const float alpha = 1.4142135623730951f;
;     float* Cw = (float*)(lds + 65536) + w * (16 * 68);
;     const int mr = m0 < MLAT ? (m0 >> 11) : 16;
;     const int colw = n0 + wn * 64;
;     const float* gate = p.mod + (size_t)(l * 17 + mr) * 3072 + 2048 + colw;
;     const float* xr = ((l == 0) ? (m0 < MLAT ? p.x + (size_t)m0 * 1024 : p.ctx + (size_t)(m0 - MLAT) * 1024)
;                                 : p.out + (size_t)m0 * 1024) + (size_t)(wm * 128) * 1024 + colw;
;     float* Z = (float*)p.slab + (size_t)(m0 + wm * 128) * 1024 + colw;
;     const int c4 = (lane & 15) * 4, rr0 = lane >> 4;
;     const float4 gt = *(const float4*)(gate + c4);
;     float4 xn[4];
; #pragma unroll
;     for (int i = 0; i < 4; ++i) xn[i] = *(const float4*)(xr + (size_t)(rr0 + 4 * i) * 1024 + c4);
; #pragma unroll
;     for (int mi = 0; mi < 8; ++mi) {
;       float4 xv[4];
; #pragma unroll
;       for (int i = 0; i < 4; ++i) xv[i] = xn[i];
;       if (mi < 7) {
; #pragma unroll
;         for (int i = 0; i < 4; ++i) xn[i] = *(const float4*)(xr + (size_t)((mi + 1) * 16 + rr0 + 4 * i) * 1024 + c4);
;       }
; #pragma unroll
;       for (int ni = 0; ni < 4; ++ni)
; #pragma unroll
;         for (int j = 0; j < 4; ++j) Cw[(g * 4 + j) * 68 + ni * 16 + r] = acc[mi][ni][j];
	v_mfma_f32_16x16x32_bf16 v[122:125], v[22:25], v[2:5], v[42:45]
	v_mfma_f32_16x16x32_bf16 v[126:129], v[22:25], v[6:9], v[46:49]
	v_mfma_f32_16x16x32_bf16 v[114:117], v[22:25], v[10:13], v[50:53]
	v_mfma_f32_16x16x32_bf16 v[118:121], v[22:25], v[14:17], v[54:57]
	ds_read_b128 v[22:25], v233 offset:6144
	s_waitcnt lgkmcnt(0)
	v_mfma_f32_16x16x32_bf16 v[78:81], v[22:25], v[2:5], v[58:61]
	v_mfma_f32_16x16x32_bf16 v[82:85], v[22:25], v[6:9], v[62:65]
	v_mfma_f32_16x16x32_bf16 v[70:73], v[22:25], v[10:13], v[66:69]
	v_mfma_f32_16x16x32_bf16 v[74:77], v[22:25], v[14:17], v[162:165]
	ds_read_b128 v[22:25], v233 offset:8192
	s_nop 1
	ds_read_b128 v[162:165], v233 offset:14336
	s_waitcnt lgkmcnt(1)
	v_mfma_f32_16x16x32_bf16 v[62:65], v[22:25], v[2:5], v[182:185]
	v_mfma_f32_16x16x32_bf16 v[66:69], v[22:25], v[6:9], v[186:189]
	v_mfma_f32_16x16x32_bf16 v[54:57], v[22:25], v[10:13], v[190:193]
	v_mfma_f32_16x16x32_bf16 v[58:61], v[22:25], v[14:17], v[212:215]
	ds_read_b128 v[22:25], v233 offset:10240
	s_waitcnt lgkmcnt(0)
	v_mfma_f32_16x16x32_bf16 v[46:49], v[22:25], v[2:5], v[216:219]
	v_mfma_f32_16x16x32_bf16 v[50:53], v[22:25], v[6:9], v[220:223]
	v_mfma_f32_16x16x32_bf16 v[38:41], v[22:25], v[10:13], v[234:237]
	v_mfma_f32_16x16x32_bf16 v[42:45], v[22:25], v[14:17], v[238:241]
	v_mfma_f32_16x16x32_bf16 v[30:33], v[26:29], v[2:5], v[242:245]
	v_mfma_f32_16x16x32_bf16 v[34:37], v[26:29], v[6:9], v[246:249]
	v_mfma_f32_16x16x32_bf16 v[22:25], v[26:29], v[10:13], v[250:253]
	v_mfma_f32_16x16x32_bf16 v[26:29], v[26:29], v[14:17], v[208:211]
	v_mfma_f32_16x16x32_bf16 v[166:169], v[162:165], v[2:5], v[166:169]
	v_mfma_f32_16x16x32_bf16 v[170:173], v[162:165], v[6:9], v[170:173]
	v_mfma_f32_16x16x32_bf16 v[2:5], v[162:165], v[10:13], v[174:177]
	v_mfma_f32_16x16x32_bf16 v[6:9], v[162:165], v[14:17], v[178:181]
	v_mov_b32_e32 v14, v195
	s_barrier
	s_waitcnt vmcnt(7)
	ds_write_b128 v198, v[18:21]
	s_waitcnt vmcnt(5)
	ds_write_b128 v198, v[86:89] offset:8192
	s_waitcnt vmcnt(4)
	ds_write_b128 v198, v[90:93] offset:16384
	s_waitcnt vmcnt(3)
	ds_write_b128 v198, v[94:97] offset:24576
	ds_write_b128 v198, v[98:101] offset:32768
	s_waitcnt vmcnt(2)
	ds_write_b128 v198, v[102:105] offset:40960
	s_waitcnt vmcnt(1)
	ds_write_b128 v198, v[106:109] offset:49152
	s_waitcnt vmcnt(0)
	ds_write_b128 v198, v[110:113] offset:57344
	s_movk_i32 s2, 0x1100
	v_lshrrev_b32_e32 v0, 6, v14
	v_mul_lo_u32 v19, v0, s2
	s_min_i32 s2, s60, 0x8000
	s_lshr_b32 s2, s2, 11
	s_mul_i32 s46, s50, 17
	v_and_b32_e32 v0, 0xc0, v14
	s_add_i32 s2, s2, s46
	v_readlane_b32 s64, v255, 28
	v_or_b32_e32 v0, s61, v0
	s_mul_hi_i32 s47, s2, 0x3000
	s_mulk_i32 s2, 0x3000
	v_readlane_b32 s66, v255, 30
	v_readlane_b32 s67, v255, 31
	s_add_u32 s46, s66, s2
	v_lshlrev_b64 v[10:11], 2, v[0:1]
	v_mov_b32_e32 v0, 0x8000
	s_addc_u32 s47, s67, s47
	v_sub_co_u32_e32 v0, vcc, s60, v0
	v_lshl_add_u64 v[12:13], s[46:47], 0, v[10:11]
	s_and_b64 s[46:47], vcc, exec
	v_readfirstlane_b32 s2, v0
	s_cselect_b32 s2, s60, s2
	s_cselect_b32 s48, 0, 16
	s_and_b64 s[46:47], s[0:1], exec
	s_cselect_b32 s46, s48, 0x88
	s_cselect_b32 s2, s2, s60
	s_add_u32 s46, s96, s46
	s_addc_u32 s47, s97, 0
	s_load_dwordx2 s[46:47], s[46:47], 0x0
	v_ashrrev_i32_e32 v0, 1, v14
	v_and_b32_e32 v18, 15, v14
	v_bfe_u32 v88, v14, 4, 2
	s_lshl_b64 s[48:49], s[2:3], 12
	v_and_b32_e32 v14, 0xffffff80, v0
	s_waitcnt lgkmcnt(0)
	s_add_u32 s46, s46, s48
	v_ashrrev_i32_e32 v15, 31, v14
	s_addc_u32 s47, s47, s49
	v_lshlrev_b64 v[16:17], 12, v[14:15]
	v_lshl_add_u64 v[16:17], s[46:47], 0, v[16:17]
	v_add_u32_e32 v14, s60, v14
	v_lshl_add_u64 v[16:17], v[16:17], 0, v[10:11]
	v_ashrrev_i32_e32 v15, 31, v14
	v_lshlrev_b32_e32 v0, 4, v18
	v_lshlrev_b64 v[14:15], 12, v[14:15]
	v_lshlrev_b32_e32 v20, 2, v18
	v_lshl_add_u64 v[16:17], v[16:17], 0, v[0:1]
	v_lshlrev_b32_e32 v86, 12, v88
	v_mov_b32_e32 v87, v1
	v_lshl_add_u64 v[14:15], s[100:101], 0, v[14:15]
	v_lshl_add_u64 v[162:163], v[16:17], 0, v[86:87]
	v_add3_u32 v16, s78, v19, v20
	s_movk_i32 s2, 0x440
	v_lshl_add_u64 v[12:13], v[12:13], 0, v[0:1]
	v_lshl_add_u64 v[10:11], v[14:15], 0, v[10:11]
	v_mad_u32_u24 v165, v88, s2, v16
	s_movk_i32 s2, 0x2000
	v_lshl_add_u64 v[14:15], v[10:11], 0, v[0:1]
	v_add_co_u32_e32 v10, vcc, s2, v12
	ds_write2_b32 v165, v146, v154 offset1:16
	ds_write2_b32 v165, v147, v155 offset0:68 offset1:84
	ds_write2_b32 v165, v148, v156 offset0:136 offset1:152
	ds_write2_b32 v165, v149, v157 offset0:204 offset1:220
	ds_write2_b32 v165, v150, v158 offset0:32 offset1:48
	ds_write2_b32 v165, v151, v159 offset0:100 offset1:116
	ds_write2_b32 v165, v152, v160 offset0:168 offset1:184
	ds_write2_b32 v165, v153, v161 offset0:236 offset1:252
	v_addc_co_u32_e32 v11, vcc, 0, v13, vcc
	v_mad_u32_u24 v17, v18, 12, v16
	global_load_dwordx4 v[18:21], v[10:11], off
	s_nop 0
	global_load_dwordx4 v[10:13], v[162:163], off
	v_or_b32_e32 v0, 4, v88
	v_add_co_u32_e32 v16, vcc, s94, v162
	v_mad_u32_u24 v164, v88, s79, v17
	v_mad_u32_u24 v158, v0, s79, v17
	v_addc_co_u32_e32 v17, vcc, 0, v163, vcc
	global_load_dwordx4 v[102:105], v[16:17], off
	v_add_co_u32_e32 v16, vcc, s21, v162
	v_lshlrev_b32_e32 v0, 12, v0
	s_nop 0
	v_addc_co_u32_e32 v17, vcc, 0, v163, vcc
	global_load_dwordx4 v[94:97], v[16:17], off
	v_lshl_add_u64 v[156:157], v[14:15], 0, v[0:1]
	v_or_b32_e32 v0, 0x8000, v86
	v_lshl_add_u64 v[154:155], v[14:15], 0, v[0:1]
	v_or_b32_e32 v0, 0xc000, v86
	s_mov_b32 s2, 0xc000
	v_lshl_add_u64 v[152:153], v[14:15], 0, v[86:87]
	v_lshl_add_u64 v[150:151], v[14:15], 0, v[0:1]
	v_add_co_u32_e32 v14, vcc, s2, v162
	s_mov_b32 s2, 0x14000
	s_nop 0
	v_addc_co_u32_e32 v15, vcc, 0, v163, vcc
	global_load_dwordx4 v[86:89], v[14:15], off
	v_add_co_u32_e32 v14, vcc, s85, v162
	s_mov_b32 s46, 0x30000
	s_nop 0
	v_addc_co_u32_e32 v15, vcc, 0, v163, vcc
	global_load_dwordx4 v[146:149], v[14:15], off
	v_add_co_u32_e32 v14, vcc, s2, v162
	s_mov_b32 s2, 0x18000
	s_nop 0
	v_addc_co_u32_e32 v15, vcc, 0, v163, vcc
	global_load_dwordx4 v[106:109], v[14:15], off
	v_add_co_u32_e32 v14, vcc, s2, v162
	s_mov_b32 s2, 0x1c000
	s_nop 0
	v_addc_co_u32_e32 v15, vcc, 0, v163, vcc
	global_load_dwordx4 v[98:101], v[14:15], off
	v_add_co_u32_e32 v14, vcc, s2, v162
	s_mov_b32 s2, 0x24000
	s_nop 0
	v_addc_co_u32_e32 v15, vcc, 0, v163, vcc
	global_load_dwordx4 v[90:93], v[14:15], off
	ds_read_b128 v[14:17], v164
	s_mov_b32 s60, s58
	s_mov_b32 s61, s59
	s_mov_b64 s[48:49], s[42:43]
	v_readlane_b32 s65, v255, 29
	v_readlane_b32 s68, v255, 32
	v_readlane_b32 s69, v255, 33
	v_readlane_b32 s70, v255, 34
	v_readlane_b32 s71, v255, 35
	s_waitcnt vmcnt(8) lgkmcnt(0)
; template <int EPI>
; DI void gemm_phase(const P& p, int l, const u16* __restrict__ A, const u16* __restrict__ Bt, int mpx, char* lds) {
;     ...
;     for (int mi = 0; mi < 8; ++mi) {
;       float4 xv[4];
; #pragma unroll
;       for (int i = 0; i < 4; ++i) xv[i] = xn[i];
;       if (mi < 7) {
; #pragma unroll
;         for (int i = 0; i < 4; ++i) xn[i] = *(const float4*)(xr + (size_t)((mi + 1) * 16 + rr0 + 4 * i) * 1024 + c4);
;       }
; #pragma unroll
;       for (int ni = 0; ni < 4; ++ni)
; #pragma unroll
;         for (int j = 0; j < 4; ++j) Cw[(g * 4 + j) * 68 + ni * 16 + r] = acc[mi][ni][j];
;       __builtin_amdgcn_fence(__ATOMIC_RELEASE, "wavefront");
; #pragma unroll
;       for (int i = 0; i < 4; ++i) {
;         const int row = rr0 + 4 * i;
;         const float4 a = *(const float4*)&Cw[row * 68 + c4];
;         float4 z;
;         z.x = alpha * xv[i].x + gt.x * a.x;
;         z.y = alpha * xv[i].y + gt.y * a.y;
;         z.z = alpha * xv[i].z + gt.z * a.z;
;         z.w = alpha * xv[i].w + gt.w * a.w;
;         *(float4*)(Z + (size_t)(mi * 16 + row) * 1024 + c4) = z;
;       }
;       __builtin_amdgcn_fence(__ATOMIC_RELEASE, "wavefront");
	v_pk_mul_f32 v[14:15], v[18:19], v[14:15]
	s_waitcnt vmcnt(7)
	v_pk_fma_f32 v[10:11], v[10:11], s[34:35], v[14:15] op_sel_hi:[1,0,1]
	v_pk_mul_f32 v[14:15], v[20:21], v[16:17]
	s_nop 0
	v_pk_fma_f32 v[12:13], v[12:13], s[34:35], v[14:15] op_sel_hi:[1,0,1]
	global_store_dwordx4 v[152:153], v[10:13], off sc1
	ds_read_b128 v[10:13], v158
	s_waitcnt lgkmcnt(0)
	v_pk_mul_f32 v[10:11], v[18:19], v[10:11]
	v_pk_mul_f32 v[12:13], v[20:21], v[12:13]
	s_waitcnt vmcnt(7)
	v_pk_fma_f32 v[10:11], v[102:103], s[34:35], v[10:11] op_sel_hi:[1,0,1]
	v_pk_fma_f32 v[12:13], v[104:105], s[34:35], v[12:13] op_sel_hi:[1,0,1]
	global_store_dwordx4 v[156:157], v[10:13], off sc1
	ds_read_b128 v[10:13], v158 offset:1088
	s_waitcnt lgkmcnt(0)
	v_pk_mul_f32 v[10:11], v[18:19], v[10:11]
	v_pk_mul_f32 v[12:13], v[20:21], v[12:13]
	s_waitcnt vmcnt(7)
	v_pk_fma_f32 v[10:11], v[94:95], s[34:35], v[10:11] op_sel_hi:[1,0,1]
	v_pk_fma_f32 v[12:13], v[96:97], s[34:35], v[12:13] op_sel_hi:[1,0,1]
	global_store_dwordx4 v[154:155], v[10:13], off sc1
	ds_read_b128 v[10:13], v158 offset:2176
	s_waitcnt lgkmcnt(0)
	v_pk_mul_f32 v[10:11], v[18:19], v[10:11]
	v_pk_mul_f32 v[12:13], v[20:21], v[12:13]
	s_waitcnt vmcnt(7)
	v_pk_fma_f32 v[10:11], v[86:87], s[34:35], v[10:11] op_sel_hi:[1,0,1]
	v_pk_fma_f32 v[12:13], v[88:89], s[34:35], v[12:13] op_sel_hi:[1,0,1]
	global_store_dwordx4 v[150:151], v[10:13], off sc1
	ds_write2_b32 v165, v138, v142 offset1:16
	ds_write2_b32 v165, v139, v143 offset0:68 offset1:84
	ds_write2_b32 v165, v140, v144 offset0:136 offset1:152
	ds_write2_b32 v165, v141, v145 offset0:204 offset1:220
	ds_write2_b32 v165, v130, v134 offset0:32 offset1:48
	ds_write2_b32 v165, v131, v135 offset0:100 offset1:116
	ds_write2_b32 v165, v132, v136 offset0:168 offset1:184
	ds_write2_b32 v165, v133, v137 offset0:236 offset1:252
	v_add_co_u32_e32 v10, vcc, s33, v162
	s_nop 1
	v_addc_co_u32_e32 v11, vcc, 0, v163, vcc
	global_load_dwordx4 v[110:113], v[10:11], off
	v_add_co_u32_e32 v10, vcc, s2, v162
	s_mov_b32 s2, 0x28000
	s_nop 0
	v_addc_co_u32_e32 v11, vcc, 0, v163, vcc
	global_load_dwordx4 v[102:105], v[10:11], off
	v_add_co_u32_e32 v10, vcc, s2, v162
	s_mov_b32 s2, 0x2c000
	s_nop 0
	v_addc_co_u32_e32 v11, vcc, 0, v163, vcc
	global_load_dwordx4 v[94:97], v[10:11], off
	v_add_co_u32_e32 v10, vcc, s2, v162
	s_mov_b32 s2, 0x34000
	s_nop 0
	v_addc_co_u32_e32 v11, vcc, 0, v163, vcc
	global_load_dwordx4 v[86:89], v[10:11], off
	ds_read_b128 v[10:13], v164
	v_add_co_u32_e32 v14, vcc, s85, v152
	s_waitcnt lgkmcnt(0)
	v_pk_mul_f32 v[10:11], v[18:19], v[10:11]
	v_pk_mul_f32 v[12:13], v[20:21], v[12:13]
	s_waitcnt vmcnt(11)
	v_pk_fma_f32 v[10:11], v[146:147], s[34:35], v[10:11] op_sel_hi:[1,0,1]
	v_pk_fma_f32 v[12:13], v[148:149], s[34:35], v[12:13] op_sel_hi:[1,0,1]
	v_addc_co_u32_e32 v15, vcc, 0, v153, vcc
	global_store_dwordx4 v[14:15], v[10:13], off sc1
	ds_read_b128 v[10:13], v158
	v_add_co_u32_e32 v14, vcc, s85, v156
	s_waitcnt lgkmcnt(0)
	v_pk_mul_f32 v[10:11], v[18:19], v[10:11]
	v_pk_mul_f32 v[12:13], v[20:21], v[12:13]
	s_waitcnt vmcnt(11)
	v_pk_fma_f32 v[10:11], v[106:107], s[34:35], v[10:11] op_sel_hi:[1,0,1]
	v_pk_fma_f32 v[12:13], v[108:109], s[34:35], v[12:13] op_sel_hi:[1,0,1]
	v_addc_co_u32_e32 v15, vcc, 0, v157, vcc
	global_store_dwordx4 v[14:15], v[10:13], off sc1
	ds_read_b128 v[10:13], v158 offset:1088
	v_add_co_u32_e32 v14, vcc, s85, v154
	s_waitcnt lgkmcnt(0)
	v_pk_mul_f32 v[10:11], v[18:19], v[10:11]
	v_pk_mul_f32 v[12:13], v[20:21], v[12:13]
	s_waitcnt vmcnt(11)
	v_pk_fma_f32 v[10:11], v[98:99], s[34:35], v[10:11] op_sel_hi:[1,0,1]
	v_pk_fma_f32 v[12:13], v[100:101], s[34:35], v[12:13] op_sel_hi:[1,0,1]
	v_addc_co_u32_e32 v15, vcc, 0, v155, vcc
	global_store_dwordx4 v[14:15], v[10:13], off sc1
	ds_read_b128 v[10:13], v158 offset:2176
	v_add_co_u32_e32 v14, vcc, s85, v150
	s_waitcnt lgkmcnt(0)
	v_pk_mul_f32 v[10:11], v[18:19], v[10:11]
	v_pk_mul_f32 v[12:13], v[20:21], v[12:13]
	s_waitcnt vmcnt(11)
	v_pk_fma_f32 v[10:11], v[90:91], s[34:35], v[10:11] op_sel_hi:[1,0,1]
	v_pk_fma_f32 v[12:13], v[92:93], s[34:35], v[12:13] op_sel_hi:[1,0,1]
	v_addc_co_u32_e32 v15, vcc, 0, v151, vcc
	global_store_dwordx4 v[14:15], v[10:13], off sc1
	ds_write2_b32 v165, v122, v126 offset1:16
	ds_write2_b32 v165, v123, v127 offset0:68 offset1:84
	ds_write2_b32 v165, v124, v128 offset0:136 offset1:152
	ds_write2_b32 v165, v125, v129 offset0:204 offset1:220
	ds_write2_b32 v165, v114, v118 offset0:32 offset1:48
	ds_write2_b32 v165, v115, v119 offset0:100 offset1:116
	ds_write2_b32 v165, v116, v120 offset0:168 offset1:184
	ds_write2_b32 v165, v117, v121 offset0:236 offset1:252
	v_add_co_u32_e32 v10, vcc, s46, v162
	s_nop 1
	v_addc_co_u32_e32 v11, vcc, 0, v163, vcc
	global_load_dwordx4 v[114:117], v[10:11], off
	v_add_co_u32_e32 v10, vcc, s2, v162
	s_mov_b32 s2, 0x38000
	s_nop 0
	v_addc_co_u32_e32 v11, vcc, 0, v163, vcc
	global_load_dwordx4 v[106:109], v[10:11], off
	v_add_co_u32_e32 v10, vcc, s2, v162
	s_mov_b32 s2, 0x3c000
	s_nop 0
	v_addc_co_u32_e32 v11, vcc, 0, v163, vcc
	global_load_dwordx4 v[98:101], v[10:11], off
	v_add_co_u32_e32 v10, vcc, s2, v162
	s_mov_b32 s2, 0x44000
	s_nop 0
	v_addc_co_u32_e32 v11, vcc, 0, v163, vcc
	global_load_dwordx4 v[90:93], v[10:11], off
	ds_read_b128 v[10:13], v164
	v_add_co_u32_e32 v14, vcc, s33, v152
	s_waitcnt lgkmcnt(0)
	v_pk_mul_f32 v[10:11], v[18:19], v[10:11]
	v_pk_mul_f32 v[12:13], v[20:21], v[12:13]
	s_waitcnt vmcnt(11)
	v_pk_fma_f32 v[10:11], v[110:111], s[34:35], v[10:11] op_sel_hi:[1,0,1]
	v_pk_fma_f32 v[12:13], v[112:113], s[34:35], v[12:13] op_sel_hi:[1,0,1]
	v_addc_co_u32_e32 v15, vcc, 0, v153, vcc
	global_store_dwordx4 v[14:15], v[10:13], off sc1
	ds_read_b128 v[10:13], v158
	v_add_co_u32_e32 v14, vcc, s33, v156
	s_waitcnt lgkmcnt(0)
; template <int EPI>
; DI void gemm_phase(const P& p, int l, const u16* __restrict__ A, const u16* __restrict__ Bt, int mpx, char* lds) {
;     ...
;     for (int mi = 0; mi < 8; ++mi) {
;       float4 xv[4];
; #pragma unroll
;       for (int i = 0; i < 4; ++i) xv[i] = xn[i];
;       if (mi < 7) {
; #pragma unroll
;         for (int i = 0; i < 4; ++i) xn[i] = *(const float4*)(xr + (size_t)((mi + 1) * 16 + rr0 + 4 * i) * 1024 + c4);
;       }
; #pragma unroll
;       for (int ni = 0; ni < 4; ++ni)
; #pragma unroll
;         for (int j = 0; j < 4; ++j) Cw[(g * 4 + j) * 68 + ni * 16 + r] = acc[mi][ni][j];
;       __builtin_amdgcn_fence(__ATOMIC_RELEASE, "wavefront");
; #pragma unroll
;       for (int i = 0; i < 4; ++i) {
;         const int row = rr0 + 4 * i;
;         const float4 a = *(const float4*)&Cw[row * 68 + c4];
;         float4 z;
;         z.x = alpha * xv[i].x + gt.x * a.x;
;         z.y = alpha * xv[i].y + gt.y * a.y;
;         z.z = alpha * xv[i].z + gt.z * a.z;
;         z.w = alpha * xv[i].w + gt.w * a.w;
;         *(float4*)(Z + (size_t)(mi * 16 + row) * 1024 + c4) = z;
;       }
;       __builtin_amdgcn_fence(__ATOMIC_RELEASE, "wavefront");
	v_pk_mul_f32 v[10:11], v[18:19], v[10:11]
	v_pk_mul_f32 v[12:13], v[20:21], v[12:13]
	s_waitcnt vmcnt(11)
	v_pk_fma_f32 v[10:11], v[102:103], s[34:35], v[10:11] op_sel_hi:[1,0,1]
	v_pk_fma_f32 v[12:13], v[104:105], s[34:35], v[12:13] op_sel_hi:[1,0,1]
	v_addc_co_u32_e32 v15, vcc, 0, v157, vcc
	global_store_dwordx4 v[14:15], v[10:13], off sc1
	ds_read_b128 v[10:13], v158 offset:1088
	v_add_co_u32_e32 v14, vcc, s33, v154
	s_waitcnt lgkmcnt(0)
	v_pk_mul_f32 v[10:11], v[18:19], v[10:11]
	v_pk_mul_f32 v[12:13], v[20:21], v[12:13]
	s_waitcnt vmcnt(11)
	v_pk_fma_f32 v[10:11], v[94:95], s[34:35], v[10:11] op_sel_hi:[1,0,1]
	v_pk_fma_f32 v[12:13], v[96:97], s[34:35], v[12:13] op_sel_hi:[1,0,1]
	v_addc_co_u32_e32 v15, vcc, 0, v155, vcc
	global_store_dwordx4 v[14:15], v[10:13], off sc1
	ds_read_b128 v[10:13], v158 offset:2176
	v_add_co_u32_e32 v14, vcc, s33, v150
	s_waitcnt lgkmcnt(0)
	v_pk_mul_f32 v[10:11], v[18:19], v[10:11]
	v_pk_mul_f32 v[12:13], v[20:21], v[12:13]
	s_waitcnt vmcnt(11)
	v_pk_fma_f32 v[10:11], v[86:87], s[34:35], v[10:11] op_sel_hi:[1,0,1]
	v_pk_fma_f32 v[12:13], v[88:89], s[34:35], v[12:13] op_sel_hi:[1,0,1]
	v_addc_co_u32_e32 v15, vcc, 0, v151, vcc
	global_store_dwordx4 v[14:15], v[10:13], off sc1
	ds_write2_b32 v165, v78, v82 offset1:16
	ds_write2_b32 v165, v79, v83 offset0:68 offset1:84
	ds_write2_b32 v165, v80, v84 offset0:136 offset1:152
	ds_write2_b32 v165, v81, v85 offset0:204 offset1:220
	ds_write2_b32 v165, v70, v74 offset0:32 offset1:48
	ds_write2_b32 v165, v71, v75 offset0:100 offset1:116
	ds_write2_b32 v165, v72, v76 offset0:168 offset1:184
	ds_write2_b32 v165, v73, v77 offset0:236 offset1:252
	v_add_co_u32_e32 v10, vcc, s35, v162
	s_nop 1
	v_addc_co_u32_e32 v11, vcc, 0, v163, vcc
	global_load_dwordx4 v[82:85], v[10:11], off
	v_add_co_u32_e32 v10, vcc, s2, v162
	s_mov_b32 s2, 0x48000
	s_nop 0
	v_addc_co_u32_e32 v11, vcc, 0, v163, vcc
	global_load_dwordx4 v[78:81], v[10:11], off
	v_add_co_u32_e32 v10, vcc, s2, v162
	s_mov_b32 s2, 0x4c000
	s_nop 0
	v_addc_co_u32_e32 v11, vcc, 0, v163, vcc
	global_load_dwordx4 v[74:77], v[10:11], off
	v_add_co_u32_e32 v10, vcc, s2, v162
	s_mov_b32 s2, 0x54000
	s_nop 0
	v_addc_co_u32_e32 v11, vcc, 0, v163, vcc
	global_load_dwordx4 v[70:73], v[10:11], off
	ds_read_b128 v[10:13], v164
	v_add_co_u32_e32 v14, vcc, s46, v152
	s_waitcnt lgkmcnt(0)
	v_pk_mul_f32 v[10:11], v[18:19], v[10:11]
	v_pk_mul_f32 v[12:13], v[20:21], v[12:13]
	s_waitcnt vmcnt(11)
	v_pk_fma_f32 v[10:11], v[114:115], s[34:35], v[10:11] op_sel_hi:[1,0,1]
	v_pk_fma_f32 v[12:13], v[116:117], s[34:35], v[12:13] op_sel_hi:[1,0,1]
	v_addc_co_u32_e32 v15, vcc, 0, v153, vcc
	global_store_dwordx4 v[14:15], v[10:13], off sc1
	ds_read_b128 v[10:13], v158
	v_add_co_u32_e32 v14, vcc, s46, v156
	s_waitcnt lgkmcnt(0)
	v_pk_mul_f32 v[10:11], v[18:19], v[10:11]
	v_pk_mul_f32 v[12:13], v[20:21], v[12:13]
	s_waitcnt vmcnt(11)
	v_pk_fma_f32 v[10:11], v[106:107], s[34:35], v[10:11] op_sel_hi:[1,0,1]
	v_pk_fma_f32 v[12:13], v[108:109], s[34:35], v[12:13] op_sel_hi:[1,0,1]
	v_addc_co_u32_e32 v15, vcc, 0, v157, vcc
	global_store_dwordx4 v[14:15], v[10:13], off sc1
	ds_read_b128 v[10:13], v158 offset:1088
	v_add_co_u32_e32 v14, vcc, s46, v154
	s_waitcnt lgkmcnt(0)
	v_pk_mul_f32 v[10:11], v[18:19], v[10:11]
	v_pk_mul_f32 v[12:13], v[20:21], v[12:13]
	s_waitcnt vmcnt(11)
	v_pk_fma_f32 v[10:11], v[98:99], s[34:35], v[10:11] op_sel_hi:[1,0,1]
	v_pk_fma_f32 v[12:13], v[100:101], s[34:35], v[12:13] op_sel_hi:[1,0,1]
	v_addc_co_u32_e32 v15, vcc, 0, v155, vcc
	global_store_dwordx4 v[14:15], v[10:13], off sc1
	ds_read_b128 v[10:13], v158 offset:2176
	v_add_co_u32_e32 v14, vcc, s46, v150
	s_mov_b32 s46, 0x50000
	s_nop 0
	v_addc_co_u32_e32 v15, vcc, 0, v151, vcc
	s_waitcnt lgkmcnt(0)
	v_pk_mul_f32 v[10:11], v[18:19], v[10:11]
	v_pk_mul_f32 v[12:13], v[20:21], v[12:13]
	s_waitcnt vmcnt(11)
	v_pk_fma_f32 v[10:11], v[90:91], s[34:35], v[10:11] op_sel_hi:[1,0,1]
	v_pk_fma_f32 v[12:13], v[92:93], s[34:35], v[12:13] op_sel_hi:[1,0,1]
	global_store_dwordx4 v[14:15], v[10:13], off sc1
	ds_write2_b32 v165, v62, v66 offset1:16
	ds_write2_b32 v165, v63, v67 offset0:68 offset1:84
	ds_write2_b32 v165, v64, v68 offset0:136 offset1:152
	ds_write2_b32 v165, v65, v69 offset0:204 offset1:220
	ds_write2_b32 v165, v54, v58 offset0:32 offset1:48
	ds_write2_b32 v165, v55, v59 offset0:100 offset1:116
	ds_write2_b32 v165, v56, v60 offset0:168 offset1:184
	ds_write2_b32 v165, v57, v61 offset0:236 offset1:252
	v_add_co_u32_e32 v10, vcc, s46, v162
	s_nop 1
	v_addc_co_u32_e32 v11, vcc, 0, v163, vcc
	global_load_dwordx4 v[66:69], v[10:11], off
	v_add_co_u32_e32 v10, vcc, s2, v162
	s_mov_b32 s2, 0x58000
	s_nop 0
	v_addc_co_u32_e32 v11, vcc, 0, v163, vcc
	global_load_dwordx4 v[62:65], v[10:11], off
	v_add_co_u32_e32 v10, vcc, s2, v162
	s_mov_b32 s2, 0x5c000
	s_nop 0
	v_addc_co_u32_e32 v11, vcc, 0, v163, vcc
	global_load_dwordx4 v[58:61], v[10:11], off
	v_add_co_u32_e32 v10, vcc, s2, v162
	s_mov_b32 s2, 0x64000
	s_nop 0
	v_addc_co_u32_e32 v11, vcc, 0, v163, vcc
	global_load_dwordx4 v[54:57], v[10:11], off
	ds_read_b128 v[10:13], v164
	v_add_co_u32_e32 v14, vcc, s35, v152
	s_waitcnt lgkmcnt(0)
	v_pk_mul_f32 v[10:11], v[18:19], v[10:11]
	v_pk_mul_f32 v[12:13], v[20:21], v[12:13]
	s_waitcnt vmcnt(11)
	v_pk_fma_f32 v[10:11], v[82:83], s[34:35], v[10:11] op_sel_hi:[1,0,1]
	v_pk_fma_f32 v[12:13], v[84:85], s[34:35], v[12:13] op_sel_hi:[1,0,1]
	v_addc_co_u32_e32 v15, vcc, 0, v153, vcc
	global_store_dwordx4 v[14:15], v[10:13], off sc1
	ds_read_b128 v[10:13], v158
	v_add_co_u32_e32 v14, vcc, s35, v156
	s_waitcnt lgkmcnt(0)
	v_pk_mul_f32 v[10:11], v[18:19], v[10:11]
	v_pk_mul_f32 v[12:13], v[20:21], v[12:13]
	s_waitcnt vmcnt(11)
; template <int EPI>
; DI void gemm_phase(const P& p, int l, const u16* __restrict__ A, const u16* __restrict__ Bt, int mpx, char* lds) {
;     ...
;     for (int mi = 0; mi < 8; ++mi) {
;       float4 xv[4];
; #pragma unroll
;       for (int i = 0; i < 4; ++i) xv[i] = xn[i];
;       if (mi < 7) {
; #pragma unroll
;         for (int i = 0; i < 4; ++i) xn[i] = *(const float4*)(xr + (size_t)((mi + 1) * 16 + rr0 + 4 * i) * 1024 + c4);
;       }
; #pragma unroll
;       for (int ni = 0; ni < 4; ++ni)
; #pragma unroll
;         for (int j = 0; j < 4; ++j) Cw[(g * 4 + j) * 68 + ni * 16 + r] = acc[mi][ni][j];
;       __builtin_amdgcn_fence(__ATOMIC_RELEASE, "wavefront");
; #pragma unroll
;       for (int i = 0; i < 4; ++i) {
;         const int row = rr0 + 4 * i;
;         const float4 a = *(const float4*)&Cw[row * 68 + c4];
;         float4 z;
;         z.x = alpha * xv[i].x + gt.x * a.x;
;         z.y = alpha * xv[i].y + gt.y * a.y;
;         z.z = alpha * xv[i].z + gt.z * a.z;
;         z.w = alpha * xv[i].w + gt.w * a.w;
;         *(float4*)(Z + (size_t)(mi * 16 + row) * 1024 + c4) = z;
;       }
;       __builtin_amdgcn_fence(__ATOMIC_RELEASE, "wavefront");
	v_pk_fma_f32 v[10:11], v[78:79], s[34:35], v[10:11] op_sel_hi:[1,0,1]
	v_pk_fma_f32 v[12:13], v[80:81], s[34:35], v[12:13] op_sel_hi:[1,0,1]
	v_addc_co_u32_e32 v15, vcc, 0, v157, vcc
	global_store_dwordx4 v[14:15], v[10:13], off sc1
	ds_read_b128 v[10:13], v158 offset:1088
	v_add_co_u32_e32 v14, vcc, s35, v154
	s_waitcnt lgkmcnt(0)
	v_pk_mul_f32 v[10:11], v[18:19], v[10:11]
	v_pk_mul_f32 v[12:13], v[20:21], v[12:13]
	s_waitcnt vmcnt(11)
	v_pk_fma_f32 v[10:11], v[74:75], s[34:35], v[10:11] op_sel_hi:[1,0,1]
	v_pk_fma_f32 v[12:13], v[76:77], s[34:35], v[12:13] op_sel_hi:[1,0,1]
	v_addc_co_u32_e32 v15, vcc, 0, v155, vcc
	global_store_dwordx4 v[14:15], v[10:13], off sc1
	ds_read_b128 v[10:13], v158 offset:2176
	v_add_co_u32_e32 v14, vcc, s35, v150
	s_waitcnt lgkmcnt(0)
	v_pk_mul_f32 v[10:11], v[18:19], v[10:11]
	v_pk_mul_f32 v[12:13], v[20:21], v[12:13]
	s_waitcnt vmcnt(11)
	v_pk_fma_f32 v[10:11], v[70:71], s[34:35], v[10:11] op_sel_hi:[1,0,1]
	v_pk_fma_f32 v[12:13], v[72:73], s[34:35], v[12:13] op_sel_hi:[1,0,1]
	v_addc_co_u32_e32 v15, vcc, 0, v151, vcc
	global_store_dwordx4 v[14:15], v[10:13], off sc1
	ds_write2_b32 v165, v46, v50 offset1:16
	ds_write2_b32 v165, v47, v51 offset0:68 offset1:84
	ds_write2_b32 v165, v48, v52 offset0:136 offset1:152
	ds_write2_b32 v165, v49, v53 offset0:204 offset1:220
	ds_write2_b32 v165, v38, v42 offset0:32 offset1:48
	ds_write2_b32 v165, v39, v43 offset0:100 offset1:116
	ds_write2_b32 v165, v40, v44 offset0:168 offset1:184
	ds_write2_b32 v165, v41, v45 offset0:236 offset1:252
	v_add_co_u32_e32 v10, vcc, s39, v162
	s_nop 1
	v_addc_co_u32_e32 v11, vcc, 0, v163, vcc
	global_load_dwordx4 v[50:53], v[10:11], off
	v_add_co_u32_e32 v10, vcc, s2, v162
	s_mov_b32 s2, 0x68000
	s_nop 0
	v_addc_co_u32_e32 v11, vcc, 0, v163, vcc
	global_load_dwordx4 v[46:49], v[10:11], off
	v_add_co_u32_e32 v10, vcc, s2, v162
	s_mov_b32 s2, 0x6c000
	s_nop 0
	v_addc_co_u32_e32 v11, vcc, 0, v163, vcc
	global_load_dwordx4 v[42:45], v[10:11], off
	v_add_co_u32_e32 v10, vcc, s2, v162
	s_mov_b32 s2, 0x74000
	s_nop 0
	v_addc_co_u32_e32 v11, vcc, 0, v163, vcc
	global_load_dwordx4 v[38:41], v[10:11], off
	ds_read_b128 v[10:13], v164
	v_add_co_u32_e32 v14, vcc, s46, v152
	s_waitcnt lgkmcnt(0)
	v_pk_mul_f32 v[10:11], v[18:19], v[10:11]
	v_pk_mul_f32 v[12:13], v[20:21], v[12:13]
	s_waitcnt vmcnt(11)
	v_pk_fma_f32 v[10:11], v[66:67], s[34:35], v[10:11] op_sel_hi:[1,0,1]
	v_pk_fma_f32 v[12:13], v[68:69], s[34:35], v[12:13] op_sel_hi:[1,0,1]
	v_addc_co_u32_e32 v15, vcc, 0, v153, vcc
	global_store_dwordx4 v[14:15], v[10:13], off sc1
	ds_read_b128 v[10:13], v158
	v_add_co_u32_e32 v14, vcc, s46, v156
	s_waitcnt lgkmcnt(0)
	v_pk_mul_f32 v[10:11], v[18:19], v[10:11]
	v_pk_mul_f32 v[12:13], v[20:21], v[12:13]
	s_waitcnt vmcnt(11)
	v_pk_fma_f32 v[10:11], v[62:63], s[34:35], v[10:11] op_sel_hi:[1,0,1]
	v_pk_fma_f32 v[12:13], v[64:65], s[34:35], v[12:13] op_sel_hi:[1,0,1]
	v_addc_co_u32_e32 v15, vcc, 0, v157, vcc
	global_store_dwordx4 v[14:15], v[10:13], off sc1
	ds_read_b128 v[10:13], v158 offset:1088
	v_add_co_u32_e32 v14, vcc, s46, v154
	s_waitcnt lgkmcnt(0)
	v_pk_mul_f32 v[10:11], v[18:19], v[10:11]
	v_pk_mul_f32 v[12:13], v[20:21], v[12:13]
	s_waitcnt vmcnt(11)
	v_pk_fma_f32 v[10:11], v[58:59], s[34:35], v[10:11] op_sel_hi:[1,0,1]
	v_pk_fma_f32 v[12:13], v[60:61], s[34:35], v[12:13] op_sel_hi:[1,0,1]
	v_addc_co_u32_e32 v15, vcc, 0, v155, vcc
	global_store_dwordx4 v[14:15], v[10:13], off sc1
	ds_read_b128 v[10:13], v158 offset:2176
	v_add_co_u32_e32 v14, vcc, s46, v150
	s_mov_b32 s46, 0x70000
	s_nop 0
	v_addc_co_u32_e32 v15, vcc, 0, v151, vcc
	s_waitcnt lgkmcnt(0)
	v_pk_mul_f32 v[10:11], v[18:19], v[10:11]
	v_pk_mul_f32 v[12:13], v[20:21], v[12:13]
	s_waitcnt vmcnt(11)
	v_pk_fma_f32 v[10:11], v[54:55], s[34:35], v[10:11] op_sel_hi:[1,0,1]
	v_pk_fma_f32 v[12:13], v[56:57], s[34:35], v[12:13] op_sel_hi:[1,0,1]
	global_store_dwordx4 v[14:15], v[10:13], off sc1
	ds_write2_b32 v165, v30, v34 offset1:16
	ds_write2_b32 v165, v31, v35 offset0:68 offset1:84
	ds_write2_b32 v165, v32, v36 offset0:136 offset1:152
	ds_write2_b32 v165, v33, v37 offset0:204 offset1:220
	ds_write2_b32 v165, v22, v26 offset0:32 offset1:48
	ds_write2_b32 v165, v23, v27 offset0:100 offset1:116
	ds_write2_b32 v165, v24, v28 offset0:168 offset1:184
	ds_write2_b32 v165, v25, v29 offset0:236 offset1:252
	v_add_co_u32_e32 v10, vcc, s46, v162
	s_nop 1
	v_addc_co_u32_e32 v11, vcc, 0, v163, vcc
	global_load_dwordx4 v[10:13], v[10:11], off
	v_add_co_u32_e32 v14, vcc, s2, v162
	s_mov_b32 s2, 0x78000
	s_nop 0
	v_addc_co_u32_e32 v15, vcc, 0, v163, vcc
	global_load_dwordx4 v[30:33], v[14:15], off
	v_add_co_u32_e32 v14, vcc, s2, v162
	s_mov_b32 s2, 0x7c000
	s_nop 0
	v_addc_co_u32_e32 v15, vcc, 0, v163, vcc
	global_load_dwordx4 v[26:29], v[14:15], off
	v_add_co_u32_e32 v14, vcc, s2, v162
	s_nop 1
	v_addc_co_u32_e32 v15, vcc, 0, v163, vcc
	global_load_dwordx4 v[22:25], v[14:15], off
	ds_read_b128 v[14:17], v164
	v_add_co_u32_e32 v34, vcc, s39, v152
	s_waitcnt lgkmcnt(0)
; template <int EPI>
; DI void gemm_phase(const P& p, int l, const u16* __restrict__ A, const u16* __restrict__ Bt, int mpx, char* lds) {
;     ...
;     for (int mi = 0; mi < 8; ++mi) {
;       float4 xv[4];
; #pragma unroll
;       for (int i = 0; i < 4; ++i) xv[i] = xn[i];
;       if (mi < 7) {
; #pragma unroll
;         for (int i = 0; i < 4; ++i) xn[i] = *(const float4*)(xr + (size_t)((mi + 1) * 16 + rr0 + 4 * i) * 1024 + c4);
;       }
; #pragma unroll
;       for (int ni = 0; ni < 4; ++ni)
; #pragma unroll
;         for (int j = 0; j < 4; ++j) Cw[(g * 4 + j) * 68 + ni * 16 + r] = acc[mi][ni][j];
;       __builtin_amdgcn_fence(__ATOMIC_RELEASE, "wavefront");
; #pragma unroll
;       for (int i = 0; i < 4; ++i) {
;         const int row = rr0 + 4 * i;
;         const float4 a = *(const float4*)&Cw[row * 68 + c4];
;         float4 z;
;         z.x = alpha * xv[i].x + gt.x * a.x;
;         z.y = alpha * xv[i].y + gt.y * a.y;
;         z.z = alpha * xv[i].z + gt.z * a.z;
;         z.w = alpha * xv[i].w + gt.w * a.w;
;         *(float4*)(Z + (size_t)(mi * 16 + row) * 1024 + c4) = z;
;       }
;       __builtin_amdgcn_fence(__ATOMIC_RELEASE, "wavefront");
;     ...
;   if (!has_next) break;
;   t = tn; m0 = m1; n0 = n1; Ag = Agn; Bg = Bgn;
	v_pk_mul_f32 v[14:15], v[18:19], v[14:15]
	v_pk_mul_f32 v[16:17], v[20:21], v[16:17]
	s_waitcnt vmcnt(11)
	v_pk_fma_f32 v[14:15], v[50:51], s[34:35], v[14:15] op_sel_hi:[1,0,1]
	v_pk_fma_f32 v[16:17], v[52:53], s[34:35], v[16:17] op_sel_hi:[1,0,1]
	v_addc_co_u32_e32 v35, vcc, 0, v153, vcc
	global_store_dwordx4 v[34:35], v[14:17], off sc1
	ds_read_b128 v[14:17], v158
	v_add_co_u32_e32 v34, vcc, s39, v156
	s_waitcnt lgkmcnt(0)
	v_pk_mul_f32 v[14:15], v[18:19], v[14:15]
	v_pk_mul_f32 v[16:17], v[20:21], v[16:17]
	s_waitcnt vmcnt(11)
	v_pk_fma_f32 v[14:15], v[46:47], s[34:35], v[14:15] op_sel_hi:[1,0,1]
	v_pk_fma_f32 v[16:17], v[48:49], s[34:35], v[16:17] op_sel_hi:[1,0,1]
	v_addc_co_u32_e32 v35, vcc, 0, v157, vcc
	global_store_dwordx4 v[34:35], v[14:17], off sc1
	ds_read_b128 v[14:17], v158 offset:1088
	v_add_co_u32_e32 v34, vcc, s39, v154
	s_waitcnt lgkmcnt(0)
	v_pk_mul_f32 v[14:15], v[18:19], v[14:15]
	v_pk_mul_f32 v[16:17], v[20:21], v[16:17]
	s_waitcnt vmcnt(11)
	v_pk_fma_f32 v[14:15], v[42:43], s[34:35], v[14:15] op_sel_hi:[1,0,1]
	v_pk_fma_f32 v[16:17], v[44:45], s[34:35], v[16:17] op_sel_hi:[1,0,1]
	v_addc_co_u32_e32 v35, vcc, 0, v155, vcc
	global_store_dwordx4 v[34:35], v[14:17], off sc1
	ds_read_b128 v[14:17], v158 offset:2176
	v_add_co_u32_e32 v34, vcc, s39, v150
	s_waitcnt lgkmcnt(0)
	v_pk_mul_f32 v[14:15], v[18:19], v[14:15]
	v_pk_mul_f32 v[16:17], v[20:21], v[16:17]
	s_waitcnt vmcnt(11)
	v_pk_fma_f32 v[14:15], v[38:39], s[34:35], v[14:15] op_sel_hi:[1,0,1]
	v_pk_fma_f32 v[16:17], v[40:41], s[34:35], v[16:17] op_sel_hi:[1,0,1]
	v_addc_co_u32_e32 v35, vcc, 0, v151, vcc
	global_store_dwordx4 v[34:35], v[14:17], off sc1
	ds_write2_b32 v165, v166, v170 offset1:16
	ds_write2_b32 v165, v167, v171 offset0:68 offset1:84
	ds_write2_b32 v165, v168, v172 offset0:136 offset1:152
	ds_write2_b32 v165, v169, v173 offset0:204 offset1:220
	ds_write2_b32 v165, v2, v6 offset0:32 offset1:48
	ds_write2_b32 v165, v3, v7 offset0:100 offset1:116
	ds_write2_b32 v165, v4, v8 offset0:168 offset1:184
	ds_write2_b32 v165, v5, v9 offset0:236 offset1:252
	ds_read_b128 v[2:5], v164
	v_add_co_u32_e32 v6, vcc, s46, v152
	s_waitcnt lgkmcnt(0)
	v_pk_mul_f32 v[2:3], v[18:19], v[2:3]
	v_pk_mul_f32 v[4:5], v[20:21], v[4:5]
	v_addc_co_u32_e32 v7, vcc, 0, v153, vcc
	s_waitcnt vmcnt(7)
	v_pk_fma_f32 v[2:3], v[10:11], s[34:35], v[2:3] op_sel_hi:[1,0,1]
	v_pk_fma_f32 v[4:5], v[12:13], s[34:35], v[4:5] op_sel_hi:[1,0,1]
	global_store_dwordx4 v[6:7], v[2:5], off sc1
	ds_read_b128 v[2:5], v158
	v_add_co_u32_e32 v6, vcc, s46, v156
	s_waitcnt lgkmcnt(0)
	v_pk_mul_f32 v[2:3], v[18:19], v[2:3]
	v_pk_mul_f32 v[4:5], v[20:21], v[4:5]
	s_waitcnt vmcnt(7)
	v_pk_fma_f32 v[2:3], v[30:31], s[34:35], v[2:3] op_sel_hi:[1,0,1]
	v_pk_fma_f32 v[4:5], v[32:33], s[34:35], v[4:5] op_sel_hi:[1,0,1]
	v_addc_co_u32_e32 v7, vcc, 0, v157, vcc
	global_store_dwordx4 v[6:7], v[2:5], off sc1
	ds_read_b128 v[2:5], v158 offset:1088
	v_add_co_u32_e32 v6, vcc, s46, v154
	s_mov_b64 s[46:47], s[44:45]
	s_nop 0
	v_addc_co_u32_e32 v7, vcc, 0, v155, vcc
	s_waitcnt lgkmcnt(0)
	v_pk_mul_f32 v[2:3], v[18:19], v[2:3]
	v_pk_mul_f32 v[4:5], v[20:21], v[4:5]
	s_waitcnt vmcnt(7)
	v_pk_fma_f32 v[2:3], v[26:27], s[34:35], v[2:3] op_sel_hi:[1,0,1]
	v_pk_fma_f32 v[4:5], v[28:29], s[34:35], v[4:5] op_sel_hi:[1,0,1]
	global_store_dwordx4 v[6:7], v[2:5], off sc1
	ds_read_b128 v[2:5], v158 offset:2176
	v_add_co_u32_e32 v6, vcc, 0x70000, v150
	s_waitcnt lgkmcnt(0)
	v_pk_mul_f32 v[2:3], v[18:19], v[2:3]
	v_pk_mul_f32 v[4:5], v[20:21], v[4:5]
	v_addc_co_u32_e32 v7, vcc, 0, v151, vcc
	s_waitcnt vmcnt(7)
	v_pk_fma_f32 v[2:3], v[22:23], s[34:35], v[2:3] op_sel_hi:[1,0,1]
	v_pk_fma_f32 v[4:5], v[24:25], s[34:35], v[4:5] op_sel_hi:[1,0,1]
	s_and_b64 vcc, exec, s[40:41]
	global_store_dwordx4 v[6:7], v[2:5], off sc1
	s_cbranch_vccz .LBB0_69
	s_mov_b32 s34, 0x3fb504f3
	v_mov_b32_e32 v236, 0x358637bd
